# HGRN outputs pass: V tiles, chunk-state words and epilogue gate/gain loads hoisted to item top
# speedup vs baseline: 1.0111x; 1.0111x over previous
.LBB0_902:
	s_or_b64 exec, exec, s[0:1]
	s_waitcnt lgkmcnt(0)
	s_barrier
	ds_read_b32 v0, v3 offset:16
	s_movk_i32 s0, 0xa9f
	s_waitcnt lgkmcnt(0)
	v_cmp_lt_i32_e32 vcc, s0, v0
	v_readfirstlane_b32 s10, v0
	s_mov_b64 s[0:1], -1
	s_cbranch_vccnz .LBB0_897
	s_cmpk_gt_i32 s10, 0x21f
	s_cbranch_scc0 .LBB0_913
	s_add_i32 s0, s10, 0xfde0
	s_and_b32 s1, s0, 0xffff
	s_mul_i32 s1, s1, 0xf0f1
	s_lshr_b32 s4, s1, 22
	s_mulk_i32 s4, 0x44
	s_sub_i32 s0, s0, s4
	s_and_b32 s4, s0, 0xffff
	s_lshr_b32 s5, s1, 24
	s_mul_i32 s11, s5, 0x1100
	s_lshl_b32 s0, s4, 6
	s_add_i32 s11, s11, s0
	s_mul_i32 s0, s11, 0x1c00
	s_bfe_u32 s6, s1, 0x20016
	s_waitcnt vmcnt(10)
	v_mov_b32_e32 v58, v222
	s_add_u32 s0, s24, s0
	v_mov_b32_e32 v8, v222
	s_addc_u32 s1, s25, 0
	s_lshl_b32 s33, s6, 6
	v_and_b32_e32 v0, 63, v8
	v_or_b32_e32 v1, s33, v0
	v_ashrrev_i32_e32 v9, 6, v8
	v_lshlrev_b32_e32 v2, 1, v1
	v_lshlrev_b32_e32 v11, 4, v9
	v_lshl_add_u64 v[4:5], s[0:1], 0, v[2:3]
	v_mad_i64_i32 v[6:7], s[8:9], v11, s48, v[4:5]
	v_mad_i64_i32 v[128:129], s[8:9], v11, s48, v[4:5]
	global_load_ushort v96, v[128:129], off offset:1024
	global_load_ushort v80, v[128:129], off offset:2048
	global_load_ushort v112, v[128:129], off offset:2560
	v_or_b32_e32 v137, 1, v11
	v_mad_i64_i32 v[130:131], s[8:9], v137, s48, v[4:5]
	global_load_ushort v97, v[130:131], off offset:1024
	global_load_ushort v81, v[130:131], off offset:2048
	global_load_ushort v113, v[130:131], off offset:2560
	v_or_b32_e32 v138, 2, v11
	v_mad_i64_i32 v[132:133], s[8:9], v138, s48, v[4:5]
	global_load_ushort v98, v[132:133], off offset:1024
	global_load_ushort v82, v[132:133], off offset:2048
	global_load_ushort v114, v[132:133], off offset:2560
	v_or_b32_e32 v139, 3, v11
	v_mad_i64_i32 v[134:135], s[8:9], v139, s48, v[4:5]
	global_load_ushort v99, v[134:135], off offset:1024
	global_load_ushort v83, v[134:135], off offset:2048
	global_load_ushort v115, v[134:135], off offset:2560
	v_or_b32_e32 v136, 4, v11
	v_mad_i64_i32 v[128:129], s[8:9], v136, s48, v[4:5]
	global_load_ushort v100, v[128:129], off offset:1024
	global_load_ushort v84, v[128:129], off offset:2048
	global_load_ushort v116, v[128:129], off offset:2560
	v_or_b32_e32 v137, 5, v11
	v_mad_i64_i32 v[130:131], s[8:9], v137, s48, v[4:5]
	global_load_ushort v101, v[130:131], off offset:1024
	global_load_ushort v85, v[130:131], off offset:2048
	global_load_ushort v117, v[130:131], off offset:2560
	v_or_b32_e32 v138, 6, v11
	v_mad_i64_i32 v[132:133], s[8:9], v138, s48, v[4:5]
	global_load_ushort v102, v[132:133], off offset:1024
	global_load_ushort v86, v[132:133], off offset:2048
	global_load_ushort v118, v[132:133], off offset:2560
	v_or_b32_e32 v139, 7, v11
	v_mad_i64_i32 v[134:135], s[8:9], v139, s48, v[4:5]
	global_load_ushort v103, v[134:135], off offset:1024
	global_load_ushort v87, v[134:135], off offset:2048
	global_load_ushort v119, v[134:135], off offset:2560
	v_or_b32_e32 v136, 8, v11
	v_mad_i64_i32 v[128:129], s[8:9], v136, s48, v[4:5]
	global_load_ushort v104, v[128:129], off offset:1024
	global_load_ushort v88, v[128:129], off offset:2048
	global_load_ushort v120, v[128:129], off offset:2560
	v_or_b32_e32 v137, 9, v11
	v_mad_i64_i32 v[130:131], s[8:9], v137, s48, v[4:5]
	global_load_ushort v105, v[130:131], off offset:1024
	global_load_ushort v89, v[130:131], off offset:2048
	global_load_ushort v121, v[130:131], off offset:2560
	v_or_b32_e32 v138, 10, v11
	v_mad_i64_i32 v[132:133], s[8:9], v138, s48, v[4:5]
	global_load_ushort v106, v[132:133], off offset:1024
	global_load_ushort v90, v[132:133], off offset:2048
	global_load_ushort v122, v[132:133], off offset:2560
	v_or_b32_e32 v139, 11, v11
	v_mad_i64_i32 v[134:135], s[8:9], v139, s48, v[4:5]
	global_load_ushort v107, v[134:135], off offset:1024
	global_load_ushort v91, v[134:135], off offset:2048
	global_load_ushort v123, v[134:135], off offset:2560
	v_or_b32_e32 v136, 12, v11
	v_mad_i64_i32 v[128:129], s[8:9], v136, s48, v[4:5]
	global_load_ushort v108, v[128:129], off offset:1024
	global_load_ushort v92, v[128:129], off offset:2048
	global_load_ushort v124, v[128:129], off offset:2560
	v_or_b32_e32 v137, 13, v11
	v_mad_i64_i32 v[130:131], s[8:9], v137, s48, v[4:5]
	global_load_ushort v109, v[130:131], off offset:1024
	global_load_ushort v93, v[130:131], off offset:2048
	global_load_ushort v125, v[130:131], off offset:2560
	v_or_b32_e32 v138, 14, v11
	v_mad_i64_i32 v[132:133], s[8:9], v138, s48, v[4:5]
	global_load_ushort v110, v[132:133], off offset:1024
	global_load_ushort v94, v[132:133], off offset:2048
	global_load_ushort v126, v[132:133], off offset:2560
	v_or_b32_e32 v139, 15, v11
	v_mad_i64_i32 v[134:135], s[8:9], v139, s48, v[4:5]
	global_load_ushort v111, v[134:135], off offset:1024
	global_load_ushort v95, v[134:135], off offset:2048
	global_load_ushort v127, v[134:135], off offset:2560
	v_lshrrev_b32_e32 v180, 3, v222
	v_mul_u32_u24_e32 v180, 0x1c00, v180
	v_lshlrev_b32_e32 v181, 4, v222
	v_and_b32_e32 v181, 0x70, v181
	s_lshl_b32 s99, s6, 7
	v_add3_u32 v180, v180, v181, s99
	global_load_dwordx4 v[140:143], v180, s[0:1] offset:1536
	v_add_u32_e32 v181, 0x38000, v180
	global_load_dwordx4 v[144:147], v181, s[0:1] offset:1536
	s_lshl_b32 s98, s5, 3
	s_lshl_b32 s99, s6, 1
	s_or_b32 s98, s98, s99
	s_mulk_i32 s98, 0x44
	s_add_i32 s98, s98, s4
	s_lshl_b32 s98, s98, 14
	s_add_u32 s98, s2, s98
	s_addc_u32 s99, s3, 0
	v_bfe_u32 v182, v222, 4, 2
	v_lshlrev_b32_e32 v182, 8, v182
	v_lshrrev_b32_e32 v183, 6, v222
	v_lshl_or_b32 v182, v183, 4, v182
	v_and_b32_e32 v183, 15, v222
	v_or_b32_e32 v182, v182, v183
	v_lshlrev_b32_e32 v182, 2, v182
	global_load_dword v148, v182, s[98:99] offset:0
	global_load_dword v149, v182, s[98:99] offset:256
	global_load_dword v150, v182, s[98:99] offset:512
	global_load_dword v151, v182, s[98:99] offset:768
	s_add_u32 s98, s98, 0x1000
	s_addc_u32 s99, s99, 0
	global_load_dword v152, v182, s[98:99] offset:0
	global_load_dword v153, v182, s[98:99] offset:256
	global_load_dword v154, v182, s[98:99] offset:512
	global_load_dword v155, v182, s[98:99] offset:768
	s_add_u32 s98, s98, 0x1000
	s_addc_u32 s99, s99, 0
	global_load_dword v156, v182, s[98:99] offset:0
	global_load_dword v157, v182, s[98:99] offset:256
	global_load_dword v158, v182, s[98:99] offset:512
	global_load_dword v159, v182, s[98:99] offset:768
	s_add_u32 s98, s98, 0x1000
	s_addc_u32 s99, s99, 0
	global_load_dword v160, v182, s[98:99] offset:0
	global_load_dword v161, v182, s[98:99] offset:256
	global_load_dword v162, v182, s[98:99] offset:512
	global_load_dword v163, v182, s[98:99] offset:768
	s_add_u32 s98, s98, 0x10d000
	s_addc_u32 s99, s99, 0
	global_load_dword v164, v182, s[98:99] offset:0
	global_load_dword v165, v182, s[98:99] offset:256
	global_load_dword v166, v182, s[98:99] offset:512
	global_load_dword v167, v182, s[98:99] offset:768
	s_add_u32 s98, s98, 0x1000
	s_addc_u32 s99, s99, 0
	global_load_dword v168, v182, s[98:99] offset:0
	global_load_dword v169, v182, s[98:99] offset:256
	global_load_dword v170, v182, s[98:99] offset:512
	global_load_dword v171, v182, s[98:99] offset:768
	s_add_u32 s98, s98, 0x1000
	s_addc_u32 s99, s99, 0
	global_load_dword v172, v182, s[98:99] offset:0
	global_load_dword v173, v182, s[98:99] offset:256
	global_load_dword v174, v182, s[98:99] offset:512
	global_load_dword v175, v182, s[98:99] offset:768
	s_add_u32 s98, s98, 0x1000
	s_addc_u32 s99, s99, 0
	global_load_dword v176, v182, s[98:99] offset:0
	global_load_dword v177, v182, s[98:99] offset:256
	global_load_dword v178, v182, s[98:99] offset:512
	global_load_dword v179, v182, s[98:99] offset:768
	v_and_b32_e32 v196, 15, v222
	v_mul_u32_u24_e32 v196, 0x1c00, v196
	v_ashrrev_i32_e32 v197, 2, v222
	v_and_b32_e32 v197, -16, v197
	v_bfe_u32 v198, v222, 4, 2
	v_lshl_or_b32 v197, v198, 2, v197
	v_lshl_add_u32 v196, v197, 1, v196
	s_lshl_b32 s99, s6, 7
	v_add_u32_e32 v196, s99, v196
	global_load_dwordx2 v[184:185], v196, s[0:1] offset:3072
	v_add_u32_e32 v198, 0x1c000, v196
	global_load_dwordx2 v[186:187], v198, s[0:1] offset:3072
	v_add_u32_e32 v198, 0x38000, v196
	global_load_dwordx2 v[188:189], v198, s[0:1] offset:3072
	v_add_u32_e32 v198, 0x54000, v196
	global_load_dwordx2 v[190:191], v198, s[0:1] offset:3072
	v_lshlrev_b32_e32 v197, 2, v197
	global_load_dwordx4 v[192:195], v197, s[34:35]
	s_barrier
	s_waitcnt vmcnt(39)
	v_mov_b32_e32 v1, v80
	v_or_b32_e32 v2, 13, v11
	v_or_b32_e32 v43, 1, v11
	v_mad_i64_i32 v[24:25], s[8:9], v2, s48, v[4:5]
	v_or_b32_e32 v20, 15, v11
	s_movk_i32 s38, 0x500
	v_mul_lo_u32 v55, v9, s38
	v_or_b32_e32 v55, v55, v0
	v_lshl_add_u32 v55, v55, 1, 32
	s_movk_i32 s39, 0x50
	s_lshl_b32 s22, s6, 7
	s_movk_i32 s42, 0xa0
	s_lshl_b32 s5, s5, 3
	s_lshl_b32 s6, s6, 1
	s_or_b32 s5, s6, s5
	s_mulk_i32 s5, 0x44
	s_add_i32 s5, s5, s4
	s_lshl_b32 s4, s5, 12
	s_mov_b32 s5, s23
	v_bfe_u32 v10, v8, 4, 2
	s_lshl_b64 s[4:5], s[4:5], 2
	s_add_u32 s12, s2, s4
	s_addc_u32 s13, s3, s5
	v_and_b32_e32 v56, 15, v58
	v_bfe_u32 v57, v58, 4, 2
	v_mov_b32_e32 v2, v93
	s_waitcnt vmcnt(1)
	v_lshlrev_b32_e32 v47, 16, v1
	v_mov_b32_e32 v1, v96
	v_mad_i64_i32 v[6:7], s[8:9], v43, s48, v[4:5]
	v_add_f32_e32 v48, 0, v47
	v_mul_f32_e32 v59, 0x3fb8aa3b, v48
	v_exp_f32_e32 v59, v59
	v_mul_f32_e32 v47, 0x3fb8aa3b, v47
	v_exp_f32_e32 v47, v47
	s_waitcnt vmcnt(0)
	v_lshlrev_b32_e32 v46, 16, v1
	v_mov_b32_e32 v1, v81
	v_mul_f32_e32 v46, v59, v46
	v_cvt_pk_bf16_f32 v46, v46, s0
	ds_write_b16 v55, v46
	v_min_f32_e64 v46, -v48, s40
	v_mul_f32_e32 v46, 0x3fb8aa3b, v46
	v_exp_f32_e32 v46, v46
	v_sub_f32_e32 v47, 1.0, v47
	v_mul_f32_e32 v46, v47, v46
	v_cvt_pk_bf16_f32 v46, v46, s0
	ds_write_b16 v55, v46 offset:10240
	s_waitcnt vmcnt(0)
	v_lshlrev_b32_e32 v44, 16, v1
	v_mov_b32_e32 v1, v97
	v_add_f32_e32 v49, v48, v44
	v_mul_f32_e32 v44, 0x3fb8aa3b, v44
	v_exp_f32_e32 v44, v44
	s_waitcnt vmcnt(0)
	v_lshlrev_b32_e32 v42, 16, v1
	v_or_b32_e32 v1, 2, v11
	v_mad_i64_i32 v[6:7], s[8:9], v1, s48, v[4:5]
	v_mov_b32_e32 v1, v82
	v_sub_f32_e32 v44, 1.0, v44
	s_waitcnt vmcnt(0)
	v_lshlrev_b32_e32 v40, 16, v1
	v_mov_b32_e32 v1, v98
	v_add_f32_e32 v50, v49, v40
	v_mul_f32_e32 v40, 0x3fb8aa3b, v40
	v_exp_f32_e32 v40, v40
	s_waitcnt vmcnt(0)
	v_lshlrev_b32_e32 v39, 16, v1
	v_or_b32_e32 v1, 3, v11
	v_mad_i64_i32 v[6:7], s[8:9], v1, s48, v[4:5]
	v_mov_b32_e32 v1, v83
	v_sub_f32_e32 v40, 1.0, v40
	s_waitcnt vmcnt(0)
	v_lshlrev_b32_e32 v38, 16, v1
	v_mov_b32_e32 v1, v99
	v_add_f32_e32 v51, v50, v38
	v_mul_f32_e32 v38, 0x3fb8aa3b, v38
	v_exp_f32_e32 v38, v38
	s_waitcnt vmcnt(0)
	v_lshlrev_b32_e32 v36, 16, v1
	v_or_b32_e32 v1, 4, v11
	v_mad_i64_i32 v[6:7], s[8:9], v1, s48, v[4:5]
	v_mov_b32_e32 v1, v84
	v_sub_f32_e32 v38, 1.0, v38
	s_waitcnt vmcnt(0)
	v_lshlrev_b32_e32 v35, 16, v1
	v_mov_b32_e32 v1, v100
	v_add_f32_e32 v52, v51, v35
	v_mul_f32_e32 v35, 0x3fb8aa3b, v35
	v_exp_f32_e32 v35, v35
	s_waitcnt vmcnt(0)
	v_lshlrev_b32_e32 v34, 16, v1
	v_or_b32_e32 v1, 5, v11
	v_mad_i64_i32 v[6:7], s[8:9], v1, s48, v[4:5]
	v_mov_b32_e32 v1, v85
	v_sub_f32_e32 v35, 1.0, v35
	s_waitcnt vmcnt(0)
	v_lshlrev_b32_e32 v32, 16, v1
	v_mov_b32_e32 v1, v101
	v_add_f32_e32 v53, v52, v32
	v_mul_f32_e32 v32, 0x3fb8aa3b, v32
	v_exp_f32_e32 v32, v32
	s_waitcnt vmcnt(0)
	v_lshlrev_b32_e32 v31, 16, v1
	v_or_b32_e32 v1, 6, v11
	v_mad_i64_i32 v[6:7], s[8:9], v1, s48, v[4:5]
	v_mov_b32_e32 v1, v86
	v_sub_f32_e32 v32, 1.0, v32
	s_waitcnt vmcnt(0)
	v_lshlrev_b32_e32 v30, 16, v1
	v_mov_b32_e32 v1, v102
	v_add_f32_e32 v54, v53, v30
	v_mul_f32_e32 v30, 0x3fb8aa3b, v30
	v_exp_f32_e32 v30, v30
	s_waitcnt vmcnt(0)
	v_lshlrev_b32_e32 v28, 16, v1
	v_or_b32_e32 v1, 7, v11
	v_mad_i64_i32 v[6:7], s[8:9], v1, s48, v[4:5]
	v_mov_b32_e32 v1, v87
	v_sub_f32_e32 v30, 1.0, v30
	s_waitcnt vmcnt(0)
	v_lshlrev_b32_e32 v27, 16, v1
	v_mov_b32_e32 v1, v103
	v_add_f32_e32 v45, v54, v27
	v_mul_f32_e32 v27, 0x3fb8aa3b, v27
	v_exp_f32_e32 v27, v27
	s_waitcnt vmcnt(0)
	v_lshlrev_b32_e32 v26, 16, v1
	v_or_b32_e32 v1, 8, v11
	v_mad_i64_i32 v[6:7], s[8:9], v1, s48, v[4:5]
	v_mov_b32_e32 v1, v88
	v_sub_f32_e32 v27, 1.0, v27
	s_waitcnt vmcnt(0)
	v_lshlrev_b32_e32 v23, 16, v1
	v_mov_b32_e32 v1, v104
	v_add_f32_e32 v41, v45, v23
	v_mul_f32_e32 v23, 0x3fb8aa3b, v23
	v_exp_f32_e32 v23, v23
	s_waitcnt vmcnt(0)
	v_lshlrev_b32_e32 v21, 16, v1
	v_or_b32_e32 v1, 9, v11
	v_mad_i64_i32 v[6:7], s[8:9], v1, s48, v[4:5]
	v_mov_b32_e32 v1, v89
	v_sub_f32_e32 v23, 1.0, v23
	s_waitcnt vmcnt(0)
	v_lshlrev_b32_e32 v19, 16, v1
	v_mov_b32_e32 v1, v105
	v_add_f32_e32 v37, v41, v19
	v_mul_f32_e32 v19, 0x3fb8aa3b, v19
	v_exp_f32_e32 v19, v19
	s_waitcnt vmcnt(0)
	v_lshlrev_b32_e32 v18, 16, v1
	v_or_b32_e32 v1, 10, v11
	v_mad_i64_i32 v[6:7], s[8:9], v1, s48, v[4:5]
	v_mov_b32_e32 v1, v90
	v_sub_f32_e32 v19, 1.0, v19
	s_waitcnt vmcnt(0)
	v_lshlrev_b32_e32 v17, 16, v1
	v_mov_b32_e32 v1, v106
	v_add_f32_e32 v33, v37, v17
	v_mul_f32_e32 v17, 0x3fb8aa3b, v17
	v_exp_f32_e32 v17, v17
	s_waitcnt vmcnt(0)
	v_lshlrev_b32_e32 v16, 16, v1
	v_or_b32_e32 v1, 11, v11
	v_mad_i64_i32 v[6:7], s[8:9], v1, s48, v[4:5]
	v_mov_b32_e32 v1, v91
	v_sub_f32_e32 v17, 1.0, v17
	s_waitcnt vmcnt(0)
	v_lshlrev_b32_e32 v15, 16, v1
	v_mov_b32_e32 v1, v107
	v_add_f32_e32 v29, v33, v15
	v_mul_f32_e32 v15, 0x3fb8aa3b, v15
	v_exp_f32_e32 v15, v15
	s_waitcnt vmcnt(0)
	v_lshlrev_b32_e32 v14, 16, v1
	v_or_b32_e32 v1, 12, v11
	v_mad_i64_i32 v[6:7], s[8:9], v1, s48, v[4:5]
	v_mov_b32_e32 v1, v92
	v_sub_f32_e32 v15, 1.0, v15
	s_waitcnt vmcnt(0)
	v_lshlrev_b32_e32 v13, 16, v1
	v_mov_b32_e32 v1, v108
	v_or_b32_e32 v6, 14, v11
	v_lshlrev_b32_e32 v7, 16, v2
	v_mov_b32_e32 v2, v109
	v_mad_i64_i32 v[24:25], s[8:9], v6, s48, v[4:5]
	v_mov_b32_e32 v6, v94
	s_waitcnt vmcnt(2)
	v_lshlrev_b32_e32 v1, 16, v1
	s_waitcnt vmcnt(1)
	v_lshlrev_b32_e32 v2, 16, v2
	s_waitcnt vmcnt(0)
	v_lshlrev_b32_e32 v12, 16, v6
	v_mov_b32_e32 v6, v110
	v_mad_i64_i32 v[24:25], s[8:9], v20, s48, v[4:5]
	v_mov_b32_e32 v4, v95
	v_mov_b32_e32 v5, v111
	v_add_f32_e32 v25, v29, v13
	v_add_f32_e32 v24, v25, v7
	v_add_f32_e32 v22, v24, v12
	v_mul_f32_e32 v13, 0x3fb8aa3b, v13
	v_exp_f32_e32 v13, v13
	s_waitcnt vmcnt(2)
	v_lshlrev_b32_e32 v6, 16, v6
	v_sub_f32_e32 v13, 1.0, v13
	s_waitcnt vmcnt(1)
	v_lshlrev_b32_e32 v4, 16, v4
	v_add_f32_e32 v20, v22, v4
	v_sub_f32_e32 v46, v20, v48
	v_mul_f32_e32 v46, 0x3fb8aa3b, v46
	v_exp_f32_e32 v46, v46
	s_waitcnt vmcnt(0)
	v_lshlrev_b32_e32 v5, 16, v5
	v_mul_f32_e32 v46, v47, v46
	v_cvt_pk_bf16_f32 v46, v46, s0
	ds_write_b16 v55, v46 offset:20480
	v_mad_u64_u32 v[46:47], s[8:9], v43, s39, v[0:1]
	v_mul_f32_e32 v0, 0x3fb8aa3b, v49
	v_exp_f32_e32 v0, v0
	s_nop 0
	v_mul_f32_e32 v0, v0, v42
	v_cvt_pk_bf16_f32 v42, v0, s0
	v_lshl_add_u32 v0, v46, 1, 32
	ds_write_b16 v0, v42
	v_min_f32_e64 v42, -v49, s40
	v_mul_f32_e32 v42, 0x3fb8aa3b, v42
	v_exp_f32_e32 v42, v42
	s_nop 0
	v_mul_f32_e32 v42, v44, v42
	v_cvt_pk_bf16_f32 v42, v42, s0
	ds_write_b16 v0, v42 offset:10240
	v_sub_f32_e32 v42, v20, v49
	v_mul_f32_e32 v42, 0x3fb8aa3b, v42
	v_exp_f32_e32 v42, v42
	s_nop 0
	v_mul_f32_e32 v42, v44, v42
	v_cvt_pk_bf16_f32 v42, v42, s0
	ds_write_b16 v0, v42 offset:20480
	v_mul_f32_e32 v42, 0x3fb8aa3b, v50
	v_exp_f32_e32 v42, v42
	s_nop 0
	v_mul_f32_e32 v39, v42, v39
	v_cvt_pk_bf16_f32 v39, v39, s0
	ds_write_b16 v0, v39 offset:160
	v_min_f32_e64 v39, -v50, s40
	v_mul_f32_e32 v39, 0x3fb8aa3b, v39
	v_exp_f32_e32 v39, v39
	s_nop 0
	v_mul_f32_e32 v39, v40, v39
	v_cvt_pk_bf16_f32 v39, v39, s0
	ds_write_b16 v0, v39 offset:10400
	v_sub_f32_e32 v39, v20, v50
	v_mul_f32_e32 v39, 0x3fb8aa3b, v39
	v_exp_f32_e32 v39, v39
	s_nop 0
	v_mul_f32_e32 v39, v40, v39
	v_cvt_pk_bf16_f32 v39, v39, s0
	ds_write_b16 v0, v39 offset:20640
	v_mul_f32_e32 v39, 0x3fb8aa3b, v51
	v_exp_f32_e32 v39, v39
	s_nop 0
	v_mul_f32_e32 v36, v39, v36
	v_cvt_pk_bf16_f32 v36, v36, s0
	ds_write_b16 v0, v36 offset:320
	v_min_f32_e64 v36, -v51, s40
	v_mul_f32_e32 v36, 0x3fb8aa3b, v36
	v_exp_f32_e32 v36, v36
	s_nop 0
	v_mul_f32_e32 v36, v38, v36
	v_cvt_pk_bf16_f32 v36, v36, s0
	ds_write_b16 v0, v36 offset:10560
	v_sub_f32_e32 v36, v20, v51
	v_mul_f32_e32 v36, 0x3fb8aa3b, v36
	v_exp_f32_e32 v36, v36
	s_nop 0
	v_mul_f32_e32 v36, v38, v36
	v_cvt_pk_bf16_f32 v36, v36, s0
	ds_write_b16 v0, v36 offset:20800
	v_mul_f32_e32 v36, 0x3fb8aa3b, v52
	v_exp_f32_e32 v36, v36
	v_lshlrev_b32_e32 v38, 3, v10
	v_mul_f32_e32 v34, v36, v34
	v_cvt_pk_bf16_f32 v34, v34, s0
	ds_write_b16 v0, v34 offset:480
	v_min_f32_e64 v34, -v52, s40
	v_mul_f32_e32 v34, 0x3fb8aa3b, v34
	v_exp_f32_e32 v34, v34
	s_nop 0
	v_mul_f32_e32 v34, v35, v34
	v_cvt_pk_bf16_f32 v34, v34, s0
	ds_write_b16 v0, v34 offset:10720
	v_sub_f32_e32 v34, v20, v52
	v_mul_f32_e32 v34, 0x3fb8aa3b, v34
	v_exp_f32_e32 v34, v34
	s_nop 0
	v_mul_f32_e32 v34, v35, v34
	v_cvt_pk_bf16_f32 v34, v34, s0
	ds_write_b16 v0, v34 offset:20960
	v_mul_f32_e32 v34, 0x3fb8aa3b, v53
	v_exp_f32_e32 v34, v34
	s_nop 0
	v_mul_f32_e32 v31, v34, v31
	v_cvt_pk_bf16_f32 v31, v31, s0
	ds_write_b16 v0, v31 offset:640
	v_min_f32_e64 v31, -v53, s40
	v_mul_f32_e32 v31, 0x3fb8aa3b, v31
	v_exp_f32_e32 v31, v31
	s_nop 0
	v_mul_f32_e32 v31, v32, v31
	v_cvt_pk_bf16_f32 v31, v31, s0
	ds_write_b16 v0, v31 offset:10880
	v_sub_f32_e32 v31, v20, v53
	v_mul_f32_e32 v31, 0x3fb8aa3b, v31
	v_exp_f32_e32 v31, v31
	s_nop 0
	v_mul_f32_e32 v31, v32, v31
	v_cvt_pk_bf16_f32 v31, v31, s0
	ds_write_b16 v0, v31 offset:21120
	v_mul_f32_e32 v31, 0x3fb8aa3b, v54
	v_exp_f32_e32 v31, v31
	s_nop 0
	v_mul_f32_e32 v28, v31, v28
	v_cvt_pk_bf16_f32 v28, v28, s0
	ds_write_b16 v0, v28 offset:800
	v_min_f32_e64 v28, -v54, s40
	v_mul_f32_e32 v28, 0x3fb8aa3b, v28
	v_exp_f32_e32 v28, v28
	s_nop 0
	v_mul_f32_e32 v28, v30, v28
	v_cvt_pk_bf16_f32 v28, v28, s0
	ds_write_b16 v0, v28 offset:11040
	v_sub_f32_e32 v28, v20, v54
	v_mul_f32_e32 v28, 0x3fb8aa3b, v28
	v_exp_f32_e32 v28, v28
	s_nop 0
	v_mul_f32_e32 v28, v30, v28
	v_cvt_pk_bf16_f32 v28, v28, s0
	ds_write_b16 v0, v28 offset:21280
	v_mul_f32_e32 v28, 0x3fb8aa3b, v45
	v_exp_f32_e32 v28, v28
	s_nop 0
	v_mul_f32_e32 v26, v28, v26
	v_cvt_pk_bf16_f32 v26, v26, s0
	ds_write_b16 v0, v26 offset:960
	v_min_f32_e64 v26, -v45, s40
	v_mul_f32_e32 v26, 0x3fb8aa3b, v26
	v_exp_f32_e32 v26, v26
	s_nop 0
	v_mul_f32_e32 v26, v27, v26
	v_cvt_pk_bf16_f32 v26, v26, s0
	ds_write_b16 v0, v26 offset:11200
	v_sub_f32_e32 v26, v20, v45
	v_mul_f32_e32 v26, 0x3fb8aa3b, v26
	v_exp_f32_e32 v26, v26
	s_nop 0
	v_mul_f32_e32 v26, v27, v26
	v_cvt_pk_bf16_f32 v26, v26, s0
	ds_write_b16 v0, v26 offset:21440
	v_mul_f32_e32 v26, 0x3fb8aa3b, v41
	v_exp_f32_e32 v26, v26
	s_nop 0
	v_mul_f32_e32 v21, v26, v21
	v_cvt_pk_bf16_f32 v21, v21, s0
	ds_write_b16 v0, v21 offset:1120
	v_min_f32_e64 v21, -v41, s40
	v_mul_f32_e32 v21, 0x3fb8aa3b, v21
	v_exp_f32_e32 v21, v21
	s_nop 0
	v_mul_f32_e32 v21, v23, v21
	v_cvt_pk_bf16_f32 v21, v21, s0
	ds_write_b16 v0, v21 offset:11360
	v_sub_f32_e32 v21, v20, v41
	v_mul_f32_e32 v21, 0x3fb8aa3b, v21
	v_exp_f32_e32 v21, v21
	v_mov_b64_e32 v[40:41], s[0:1]
	v_mul_f32_e32 v21, v23, v21
	v_cvt_pk_bf16_f32 v21, v21, s0
	ds_write_b16 v0, v21 offset:21600
	v_mul_f32_e32 v21, 0x3fb8aa3b, v37
	v_exp_f32_e32 v21, v21
	s_nop 0
	v_mul_f32_e32 v18, v21, v18
	v_cvt_pk_bf16_f32 v18, v18, s0
	ds_write_b16 v0, v18 offset:1280
	v_min_f32_e64 v18, -v37, s40
	v_mul_f32_e32 v18, 0x3fb8aa3b, v18
	v_exp_f32_e32 v18, v18
	s_nop 0
	v_mul_f32_e32 v18, v19, v18
	v_cvt_pk_bf16_f32 v18, v18, s0
	ds_write_b16 v0, v18 offset:11520
	v_sub_f32_e32 v18, v20, v37
	v_mul_f32_e32 v18, 0x3fb8aa3b, v18
	v_exp_f32_e32 v18, v18
	v_lshl_add_u32 v37, v9, 5, 32
	v_mul_f32_e32 v18, v19, v18
	v_cvt_pk_bf16_f32 v18, v18, s0
	ds_write_b16 v0, v18 offset:21760
	v_mul_f32_e32 v18, 0x3fb8aa3b, v33
	v_exp_f32_e32 v18, v18
	s_nop 0
	v_mul_f32_e32 v16, v18, v16
	v_cvt_pk_bf16_f32 v16, v16, s0
	ds_write_b16 v0, v16 offset:1440
	v_min_f32_e64 v16, -v33, s40
	v_mul_f32_e32 v16, 0x3fb8aa3b, v16
	v_exp_f32_e32 v16, v16
	s_nop 0
	v_mul_f32_e32 v16, v17, v16
	v_cvt_pk_bf16_f32 v16, v16, s0
	ds_write_b16 v0, v16 offset:11680
	v_sub_f32_e32 v16, v20, v33
	v_mul_f32_e32 v16, 0x3fb8aa3b, v16
	v_exp_f32_e32 v16, v16
	v_lshlrev_b32_e32 v33, 2, v10
	v_mul_f32_e32 v16, v17, v16
	v_cvt_pk_bf16_f32 v16, v16, s0
	ds_write_b16 v0, v16 offset:21920
	v_mul_f32_e32 v16, 0x3fb8aa3b, v29
	v_exp_f32_e32 v16, v16
	s_nop 0
	v_mul_f32_e32 v14, v16, v14
	v_cvt_pk_bf16_f32 v14, v14, s0
	ds_write_b16 v0, v14 offset:1600
	v_min_f32_e64 v14, -v29, s40
	v_mul_f32_e32 v14, 0x3fb8aa3b, v14
	v_exp_f32_e32 v14, v14
	s_nop 0
	v_mul_f32_e32 v14, v15, v14
	v_cvt_pk_bf16_f32 v14, v14, s0
	ds_write_b16 v0, v14 offset:11840
	v_sub_f32_e32 v14, v20, v29
	v_mul_f32_e32 v14, 0x3fb8aa3b, v14
	v_exp_f32_e32 v14, v14
	s_nop 0
	v_mul_f32_e32 v14, v15, v14
	v_cvt_pk_bf16_f32 v14, v14, s0
	ds_write_b16 v0, v14 offset:22080
	v_mul_f32_e32 v14, 0x3fb8aa3b, v25
	v_exp_f32_e32 v14, v14
	s_nop 0
	v_mul_f32_e32 v1, v14, v1
	v_cvt_pk_bf16_f32 v1, v1, s0
	ds_write_b16 v0, v1 offset:1760
	v_min_f32_e64 v1, -v25, s40
	v_mul_f32_e32 v1, 0x3fb8aa3b, v1
	v_exp_f32_e32 v1, v1
	s_nop 0
	v_mul_f32_e32 v1, v13, v1
	v_cvt_pk_bf16_f32 v1, v1, s0
	ds_write_b16 v0, v1 offset:12000
	v_sub_f32_e32 v1, v20, v25
	v_mul_f32_e32 v1, 0x3fb8aa3b, v1
	v_exp_f32_e32 v1, v1
	s_nop 0
	v_mul_f32_e32 v1, v13, v1
	v_cvt_pk_bf16_f32 v1, v1, s0
	ds_write_b16 v0, v1 offset:22240
	v_mul_f32_e32 v1, 0x3fb8aa3b, v7
	v_mul_f32_e32 v7, 0x3fb8aa3b, v24
	v_exp_f32_e32 v7, v7
	v_exp_f32_e32 v1, v1
	v_mul_f32_e32 v2, v7, v2
	v_cvt_pk_bf16_f32 v2, v2, s0
	ds_write_b16 v0, v2 offset:1920
	v_min_f32_e64 v2, -v24, s40
	v_mul_f32_e32 v2, 0x3fb8aa3b, v2
	v_exp_f32_e32 v2, v2
	v_sub_f32_e32 v1, 1.0, v1
	v_mul_f32_e32 v2, v1, v2
	v_cvt_pk_bf16_f32 v2, v2, s0
	ds_write_b16 v0, v2 offset:12160
	v_sub_f32_e32 v2, v20, v24
	v_mul_f32_e32 v2, 0x3fb8aa3b, v2
	v_exp_f32_e32 v2, v2
	s_nop 0
	v_mul_f32_e32 v1, v1, v2
	v_mul_f32_e32 v2, 0x3fb8aa3b, v22
	v_exp_f32_e32 v2, v2
	v_cvt_pk_bf16_f32 v1, v1, s0
	ds_write_b16 v0, v1 offset:22400
	v_mul_f32_e32 v1, 0x3fb8aa3b, v12
	v_mul_f32_e32 v2, v2, v6
	v_cvt_pk_bf16_f32 v2, v2, s0
	ds_write_b16 v0, v2 offset:2080
	v_min_f32_e64 v2, -v22, s40
	v_exp_f32_e32 v1, v1
	v_mul_f32_e32 v2, 0x3fb8aa3b, v2
	v_exp_f32_e32 v2, v2
	v_lshlrev_b32_e32 v12, 2, v8
	v_sub_f32_e32 v1, 1.0, v1
	v_and_b32_e32 v35, 12, v12
	v_mul_f32_e32 v2, v1, v2
	v_cvt_pk_bf16_f32 v2, v2, s0
	ds_write_b16 v0, v2 offset:12320
	v_sub_f32_e32 v2, v20, v22
	v_mul_f32_e32 v2, 0x3fb8aa3b, v2
	v_exp_f32_e32 v2, v2
	s_nop 0
	v_mul_f32_e32 v1, v1, v2
	v_mul_f32_e32 v2, 0x3fb8aa3b, v20
	v_exp_f32_e32 v2, v2
	v_cvt_pk_bf16_f32 v1, v1, s0
	ds_write_b16 v0, v1 offset:22560
	v_mul_f32_e32 v1, 0x3fb8aa3b, v4
	v_mul_f32_e32 v4, v2, v5
	v_cvt_pk_bf16_f32 v4, v4, s0
	ds_write_b16 v0, v4 offset:2240
	v_min_f32_e64 v4, -v20, s40
	v_exp_f32_e32 v1, v1
	v_mul_f32_e32 v4, 0x3fb8aa3b, v4
	v_exp_f32_e32 v4, v4
	v_sub_f32_e32 v1, 1.0, v1
	v_mul_f32_e32 v4, v1, v4
	v_cvt_pk_bf16_f32 v4, v4, s0
	ds_write_b16 v0, v4 offset:12480
	v_sub_f32_e32 v4, v20, v20
	v_mul_f32_e32 v4, 0x3fb8aa3b, v4
	v_exp_f32_e32 v4, v4
	s_nop 0
	v_mul_f32_e32 v1, v1, v4
	v_cvt_pk_bf16_f32 v1, v1, s0
	ds_write_b16 v0, v1 offset:22720
	v_add_u32_e32 v0, 32, v12
	v_ashrrev_i32_e32 v1, 3, v8
	ds_write_b32 v0, v2 offset:40960
	v_lshlrev_b32_e32 v0, 4, v8
	v_mad_i64_i32 v[4:5], s[8:9], v1, s48, v[40:41]
	v_and_b32_e32 v2, 0x70, v0
	v_lshl_add_u64 v[4:5], v[4:5], 0, s[22:23]
	v_lshl_add_u64 v[4:5], v[4:5], 0, v[2:3]
	s_waitcnt vmcnt(37)
	v_mov_b32_e32 v4, v140
	v_mov_b32_e32 v5, v141
	v_mov_b32_e32 v6, v142
	v_mov_b32_e32 v7, v143
	v_add_u32_e32 v0, 32, v2
	v_mad_u64_u32 v[14:15], s[8:9], v1, s42, v[0:1]
	v_add_u32_e32 v1, 0x100, v8
	v_ashrrev_i32_e32 v1, 3, v1
	s_waitcnt vmcnt(0)
	ds_write_b128 v14, v[4:7] offset:30720
	v_mad_i64_i32 v[4:5], s[8:9], v1, s48, v[40:41]
	v_lshl_add_u64 v[4:5], v[4:5], 0, s[22:23]
	v_lshl_add_u64 v[4:5], v[4:5], 0, v[2:3]
	v_mov_b32_e32 v4, v144
	v_mov_b32_e32 v5, v145
	v_mov_b32_e32 v6, v146
	v_mov_b32_e32 v7, v147
	v_mad_u64_u32 v[0:1], s[8:9], v1, s42, v[0:1]
	v_and_b32_e32 v2, 15, v8
	v_cmp_gt_u32_e32 vcc, v33, v2
	v_cmp_lt_u32_e64 s[4:5], v33, v2
	s_waitcnt vmcnt(0)
	ds_write_b128 v0, v[4:7] offset:30720
	v_or_b32_e32 v0, v11, v2
	v_lshl_add_u32 v0, v10, 8, v0
	v_ashrrev_i32_e32 v1, 31, v0
	v_lshl_add_u64 v[4:5], v[0:1], 2, s[12:13]
	s_waitcnt lgkmcnt(0)
	s_barrier
	s_waitcnt vmcnt(21)
	v_mov_b32_e32 v16, v148
	v_mov_b32_e32 v17, v149
	v_mov_b32_e32 v18, v150
	v_mov_b32_e32 v19, v151
	v_add_u32_e32 v4, 0x400, v0
	v_ashrrev_i32_e32 v5, 31, v4
	v_lshl_add_u64 v[4:5], v[4:5], 2, s[12:13]
	v_mov_b32_e32 v20, v152
	v_add_u32_e32 v4, 0x440, v0
	v_ashrrev_i32_e32 v5, 31, v4
	v_lshl_add_u64 v[4:5], v[4:5], 2, s[12:13]
	v_mov_b32_e32 v21, v153
	v_add_u32_e32 v4, 0x480, v0
	v_ashrrev_i32_e32 v5, 31, v4
	v_lshl_add_u64 v[4:5], v[4:5], 2, s[12:13]
	v_mov_b32_e32 v22, v154
	v_add_u32_e32 v4, 0x4c0, v0
	v_ashrrev_i32_e32 v5, 31, v4
	v_lshl_add_u64 v[4:5], v[4:5], 2, s[12:13]
	v_mov_b32_e32 v23, v155
	v_add_u32_e32 v4, 0x800, v0
	v_ashrrev_i32_e32 v5, 31, v4
	v_lshl_add_u64 v[4:5], v[4:5], 2, s[12:13]
	v_mov_b32_e32 v24, v156
	v_add_u32_e32 v4, 0x840, v0
	v_ashrrev_i32_e32 v5, 31, v4
	v_lshl_add_u64 v[4:5], v[4:5], 2, s[12:13]
	v_mov_b32_e32 v25, v157
	v_add_u32_e32 v4, 0x880, v0
	v_ashrrev_i32_e32 v5, 31, v4
	v_lshl_add_u64 v[4:5], v[4:5], 2, s[12:13]
	v_mov_b32_e32 v26, v158
	v_add_u32_e32 v4, 0x8c0, v0
	v_ashrrev_i32_e32 v5, 31, v4
	v_lshl_add_u64 v[4:5], v[4:5], 2, s[12:13]
	v_mov_b32_e32 v27, v159
	v_add_u32_e32 v4, 0xc00, v0
	v_ashrrev_i32_e32 v5, 31, v4
	v_lshl_add_u64 v[4:5], v[4:5], 2, s[12:13]
	v_mov_b32_e32 v28, v160
	v_add_u32_e32 v4, 0xc40, v0
	v_ashrrev_i32_e32 v5, 31, v4
	v_lshl_add_u64 v[4:5], v[4:5], 2, s[12:13]
	v_mov_b32_e32 v29, v161
	v_add_u32_e32 v4, 0xc80, v0
	v_add_u32_e32 v0, 0xcc0, v0
	v_ashrrev_i32_e32 v5, 31, v4
	v_ashrrev_i32_e32 v1, 31, v0
	v_lshl_add_u64 v[4:5], v[4:5], 2, s[12:13]
	v_lshl_add_u64 v[0:1], v[0:1], 2, s[12:13]
	v_mov_b32_e32 v30, v162
	v_mov_b32_e32 v31, v163
	v_bfe_u32 v0, v8, 2, 2
	v_and_b32_e32 v8, 48, v8
	v_mul_u32_u24_e32 v4, 0x50, v2
	v_add_u32_e32 v39, 32, v8
	v_lshlrev_b32_e32 v9, 1, v4
	v_add_u32_e32 v32, v39, v9
	ds_read_b128 v[4:7], v32 offset:10240
	v_add3_u32 v36, 32, v9, v8
	v_or_b32_e32 v34, v33, v0
	ds_read_b128 v[8:11], v36
	v_mul_u32_u24_e32 v0, 0x50, v34
	v_or_b32_e32 v0, v0, v35
	v_lshlrev_b32_e32 v43, 1, v0
	v_add_u32_e32 v44, v37, v43
	ds_read_b64_tr_b16 v[0:1], v44 offset:30720
	s_waitcnt lgkmcnt(1)
	v_mfma_f32_16x16x32_bf16 v[4:7], v[4:7], v[8:11], 0
	ds_read_b128 v[8:11], v32 offset:10304
	ds_read_b128 v[12:15], v36 offset:64
	v_sub_u32_e32 v42, v36, v38
	v_add_u32_e32 v38, 0x800, v42
	s_waitcnt lgkmcnt(0)
	v_mfma_f32_16x16x32_bf16 v[4:7], v[8:11], v[12:15], v[4:7]
	v_or_b32_e32 v8, 2, v33
	v_cmp_gt_u32_e64 s[6:7], v8, v2
	v_or_b32_e32 v8, 3, v33
	v_cmp_gt_u32_e64 s[8:9], v8, v2
	s_nop 3
	v_cndmask_b32_e64 v4, v4, 0, vcc
	v_cndmask_b32_e64 v5, 0, v5, s[4:5]
	v_cndmask_b32_e64 v6, v6, 0, s[6:7]
	v_cndmask_b32_e64 v2, v7, 0, s[8:9]
	v_cvt_pk_bf16_f32 v4, v4, v5
	v_cvt_pk_bf16_f32 v5, v6, v2
	v_mov_b32_e32 v2, v3
	v_mov_b32_e32 v6, v3
	v_mov_b32_e32 v7, v3
	s_waitcnt vmcnt(14)
	v_cvt_pk_bf16_f32 v8, v16, v17
	s_waitcnt vmcnt(12)
	v_cvt_pk_bf16_f32 v9, v18, v19
	ds_read2_b64 v[12:15], v42 offset1:4
	v_mfma_f32_16x16x32_bf16 v[4:7], v[0:3], v[4:7], 0
	s_waitcnt vmcnt(10)
	v_cvt_pk_bf16_f32 v10, v20, v21
	v_add_u32_e32 v33, 32, v43
	s_waitcnt vmcnt(8)
	v_cvt_pk_bf16_f32 v11, v22, v23
	s_waitcnt lgkmcnt(0)
	s_nop 0
	v_mfma_f32_16x16x32_bf16 v[4:7], v[8:11], v[12:15], v[4:7]
	ds_read2_b64 v[12:15], v42 offset0:8 offset1:12
	s_waitcnt vmcnt(6)
	v_cvt_pk_bf16_f32 v8, v24, v25
	s_waitcnt vmcnt(4)
	v_cvt_pk_bf16_f32 v9, v26, v27
	s_waitcnt vmcnt(2)
	v_cvt_pk_bf16_f32 v10, v28, v29
	s_waitcnt vmcnt(0)
	v_cvt_pk_bf16_f32 v11, v30, v31
	s_waitcnt lgkmcnt(0)
	s_nop 0
	v_mfma_f32_16x16x32_bf16 v[4:7], v[8:11], v[12:15], v[4:7]
	v_mov_b32_e32 v10, v3
	v_mov_b32_e32 v11, v3
	v_mov_b32_e32 v14, v3
	s_nop 4
	v_pk_add_f32 v[52:53], v[6:7], 0 op_sel_hi:[1,0]
	v_pk_add_f32 v[54:55], v[4:5], 0 op_sel_hi:[1,0]
	ds_read_b128 v[4:7], v39 offset:40960
	ds_read_b64_tr_b16 v[8:9], v33 offset:20480
	ds_read_b64_tr_b16 v[12:13], v33 offset:20512
	v_mov_b32_e32 v15, v3
	s_waitcnt lgkmcnt(2)
	v_pk_mul_f32 v[4:5], v[16:17], v[4:5]
	v_pk_mul_f32 v[6:7], v[18:19], v[6:7]
	ds_read_b64_tr_b16 v[16:17], v33 offset:20544
	v_mov_b32_e32 v18, v3
	s_waitcnt lgkmcnt(2)
	v_mfma_f32_16x16x32_bf16 v[8:11], v[8:11], v[0:3], v[4:7]
	v_mov_b32_e32 v19, v3
	s_nop 1
	ds_read_b128 v[4:7], v39 offset:41024
	s_waitcnt lgkmcnt(0)
	v_pk_mul_f32 v[4:5], v[20:21], v[4:5]
	v_pk_mul_f32 v[6:7], v[22:23], v[6:7]
	ds_read_b64_tr_b16 v[20:21], v33 offset:20576
	v_mov_b32_e32 v22, v3
	v_mfma_f32_16x16x32_bf16 v[12:15], v[12:15], v[0:3], v[4:7]
	v_mov_b32_e32 v23, v3
	s_nop 1
	ds_read_b128 v[4:7], v39 offset:41088
	s_waitcnt lgkmcnt(0)
	v_pk_mul_f32 v[4:5], v[24:25], v[4:5]
	v_pk_mul_f32 v[6:7], v[26:27], v[6:7]
	s_nop 1
	v_mfma_f32_16x16x32_bf16 v[16:19], v[16:19], v[0:3], v[4:7]
	s_nop 2
	ds_read_b128 v[4:7], v39 offset:41152
	s_waitcnt lgkmcnt(0)
	v_pk_mul_f32 v[4:5], v[28:29], v[4:5]
	v_pk_mul_f32 v[6:7], v[30:31], v[6:7]
	s_nop 1
	v_mfma_f32_16x16x32_bf16 v[20:23], v[20:23], v[0:3], v[4:7]
	ds_read_b64_tr_b16 v[0:1], v44 offset:33280
	s_nop 1
	ds_read_b128 v[4:7], v32 offset:12800
	ds_read_b128 v[24:27], v36 offset:2560
	s_waitcnt lgkmcnt(0)
	v_mfma_f32_16x16x32_bf16 v[4:7], v[4:7], v[24:27], 0
	ds_read_b128 v[24:27], v32 offset:12864
	ds_read_b128 v[28:31], v36 offset:2624
	s_waitcnt lgkmcnt(0)
	v_mfma_f32_16x16x32_bf16 v[4:7], v[24:27], v[28:31], v[4:7]
	v_cvt_pk_bf16_f32 v24, v8, v9
	v_cvt_pk_bf16_f32 v25, v10, v11
	v_cvt_pk_bf16_f32 v26, v12, v13
	s_nop 4
	v_cndmask_b32_e64 v2, v4, 0, vcc
	v_cndmask_b32_e64 v4, 0, v5, s[4:5]
	v_cvt_pk_bf16_f32 v4, v2, v4
	v_mov_b32_e32 v2, v3
	v_cndmask_b32_e64 v5, v6, 0, s[6:7]
	v_cndmask_b32_e64 v6, v7, 0, s[8:9]
	v_cvt_pk_bf16_f32 v5, v5, v6
	v_mov_b32_e32 v6, v3
	v_mov_b32_e32 v7, v3
	v_cvt_pk_bf16_f32 v27, v14, v15
	ds_read2_b64 v[28:31], v38 offset0:64 offset1:68
	v_mfma_f32_16x16x32_bf16 v[4:7], v[0:3], v[4:7], 0
	s_waitcnt lgkmcnt(0)
	v_mfma_f32_16x16x32_bf16 v[4:7], v[24:27], v[28:31], v[4:7]
	v_cvt_pk_bf16_f32 v24, v16, v17
	v_cvt_pk_bf16_f32 v25, v18, v19
	v_cvt_pk_bf16_f32 v26, v20, v21
	v_cvt_pk_bf16_f32 v27, v22, v23
	ds_read2_b64 v[28:31], v38 offset0:72 offset1:76
	v_add_u32_e32 v38, 0x1000, v42
	s_waitcnt lgkmcnt(0)
	v_mfma_f32_16x16x32_bf16 v[4:7], v[24:27], v[28:31], v[4:7]
	ds_read_b128 v[24:27], v39 offset:41216
	s_waitcnt lgkmcnt(0)
	v_pk_mul_f32 v[8:9], v[8:9], v[24:25]
	ds_read_b64_tr_b16 v[24:25], v33 offset:23040
	v_pk_mul_f32 v[10:11], v[10:11], v[26:27]
	v_mov_b32_e32 v26, v3
	v_mov_b32_e32 v27, v3
	s_waitcnt lgkmcnt(0)
	s_nop 0
	v_mfma_f32_16x16x32_bf16 v[24:27], v[24:27], v[0:3], v[8:11]
	s_nop 2
	ds_read_b128 v[8:11], v39 offset:41280
	s_waitcnt lgkmcnt(0)
	v_pk_mul_f32 v[8:9], v[12:13], v[8:9]
	ds_read_b64_tr_b16 v[12:13], v33 offset:23072
	v_pk_mul_f32 v[10:11], v[14:15], v[10:11]
	v_mov_b32_e32 v14, v3
	v_mov_b32_e32 v15, v3
	s_waitcnt lgkmcnt(0)
	s_nop 0
	v_mfma_f32_16x16x32_bf16 v[12:15], v[12:15], v[0:3], v[8:11]
	s_nop 2
	ds_read_b128 v[8:11], v39 offset:41344
	s_waitcnt lgkmcnt(0)
	v_pk_mul_f32 v[8:9], v[16:17], v[8:9]
	ds_read_b64_tr_b16 v[16:17], v33 offset:23104
	v_pk_mul_f32 v[10:11], v[18:19], v[10:11]
	v_mov_b32_e32 v18, v3
	v_mov_b32_e32 v19, v3
	s_waitcnt lgkmcnt(0)
	s_nop 0
	v_mfma_f32_16x16x32_bf16 v[16:19], v[16:19], v[0:3], v[8:11]
	s_nop 2
	ds_read_b128 v[8:11], v39 offset:41408
	s_waitcnt lgkmcnt(0)
	v_pk_mul_f32 v[8:9], v[20:21], v[8:9]
	ds_read_b64_tr_b16 v[20:21], v33 offset:23136
	v_pk_mul_f32 v[10:11], v[22:23], v[10:11]
	v_mov_b32_e32 v22, v3
	v_mov_b32_e32 v23, v3
	s_waitcnt lgkmcnt(0)
	s_nop 0
	v_mfma_f32_16x16x32_bf16 v[28:31], v[20:23], v[0:3], v[8:11]
	ds_read_b64_tr_b16 v[0:1], v44 offset:35840
	s_nop 1
	ds_read_b128 v[8:11], v32 offset:15360
	ds_read_b128 v[20:23], v36 offset:5120
	s_waitcnt lgkmcnt(0)
	v_mfma_f32_16x16x32_bf16 v[8:11], v[8:11], v[20:23], 0
	ds_read_b128 v[20:23], v32 offset:15424
	ds_read_b128 v[44:47], v36 offset:5184
	s_waitcnt lgkmcnt(0)
	v_mfma_f32_16x16x32_bf16 v[8:11], v[20:23], v[44:47], v[8:11]
	v_cvt_pk_bf16_f32 v20, v24, v25
	v_cvt_pk_bf16_f32 v21, v26, v27
	v_cvt_pk_bf16_f32 v22, v12, v13
	s_nop 4
	v_cndmask_b32_e64 v2, v8, 0, vcc
	v_cndmask_b32_e64 v8, 0, v9, s[4:5]
	v_cvt_pk_bf16_f32 v8, v2, v8
	v_mov_b32_e32 v2, v3
	v_cndmask_b32_e64 v9, v10, 0, s[6:7]
	v_cndmask_b32_e64 v10, v11, 0, s[8:9]
	v_cvt_pk_bf16_f32 v9, v9, v10
	v_mov_b32_e32 v10, v3
	v_mov_b32_e32 v11, v3
	v_cvt_pk_bf16_f32 v23, v14, v15
	ds_read2_b64 v[44:47], v38 offset0:128 offset1:132
	v_mfma_f32_16x16x32_bf16 v[8:11], v[0:3], v[8:11], 0
	s_waitcnt lgkmcnt(0)
	v_mfma_f32_16x16x32_bf16 v[8:11], v[20:23], v[44:47], v[8:11]
	v_cvt_pk_bf16_f32 v20, v16, v17
	v_cvt_pk_bf16_f32 v21, v18, v19
	v_cvt_pk_bf16_f32 v22, v28, v29
	v_cvt_pk_bf16_f32 v23, v30, v31
	ds_read2_b64 v[44:47], v38 offset0:136 offset1:140
	s_waitcnt lgkmcnt(0)
	v_mfma_f32_16x16x32_bf16 v[8:11], v[20:23], v[44:47], v[8:11]
	ds_read_b128 v[20:23], v39 offset:41472
	s_waitcnt lgkmcnt(0)
	v_pk_mul_f32 v[20:21], v[24:25], v[20:21]
	ds_read_b64_tr_b16 v[24:25], v33 offset:25600
	v_pk_mul_f32 v[22:23], v[26:27], v[22:23]
	v_mov_b32_e32 v26, v3
	v_mov_b32_e32 v27, v3
	s_waitcnt lgkmcnt(0)
	s_nop 0
	v_mfma_f32_16x16x32_bf16 v[20:23], v[24:27], v[0:3], v[20:23]
	ds_read_b128 v[24:27], v39 offset:41536
	s_waitcnt lgkmcnt(0)
	v_pk_mul_f32 v[12:13], v[12:13], v[24:25]
	ds_read_b64_tr_b16 v[24:25], v33 offset:25632
	v_pk_mul_f32 v[14:15], v[14:15], v[26:27]
	v_mov_b32_e32 v26, v3
	v_mov_b32_e32 v27, v3
	s_nop 0
	v_cvt_pk_bf16_f32 v20, v20, v21
	v_cvt_pk_bf16_f32 v21, v22, v23
	s_waitcnt lgkmcnt(0)
	v_mfma_f32_16x16x32_bf16 v[24:27], v[24:27], v[0:3], v[12:15]
	s_nop 2
	ds_read_b128 v[12:15], v39 offset:41600
	s_waitcnt lgkmcnt(0)
	v_pk_mul_f32 v[12:13], v[16:17], v[12:13]
	ds_read_b64_tr_b16 v[16:17], v33 offset:25664
	v_pk_mul_f32 v[14:15], v[18:19], v[14:15]
	v_mov_b32_e32 v18, v3
	v_mov_b32_e32 v19, v3
	v_cvt_pk_bf16_f32 v22, v24, v25
	v_cvt_pk_bf16_f32 v23, v26, v27
	s_waitcnt lgkmcnt(0)
	v_mfma_f32_16x16x32_bf16 v[12:15], v[16:19], v[0:3], v[12:15]
	ds_read_b128 v[16:19], v39 offset:41664
	s_waitcnt lgkmcnt(0)
	v_pk_mul_f32 v[16:17], v[28:29], v[16:17]
	ds_read_b64_tr_b16 v[28:29], v33 offset:25696
	v_pk_mul_f32 v[18:19], v[30:31], v[18:19]
	v_mov_b32_e32 v30, v3
	v_mov_b32_e32 v31, v3
	s_nop 0
	v_cvt_pk_bf16_f32 v12, v12, v13
	v_cvt_pk_bf16_f32 v13, v14, v15
	s_waitcnt lgkmcnt(0)
	v_mfma_f32_16x16x32_bf16 v[16:19], v[28:31], v[0:3], v[16:19]
	v_mul_u32_u24_e32 v0, 0xa0, v34
	v_lshlrev_b32_e32 v1, 1, v35
	v_add3_u32 v0, v37, v0, v1
	ds_read_b64_tr_b16 v[0:1], v0 offset:38400
	ds_read_b128 v[28:31], v32 offset:17920
	ds_read_b128 v[44:47], v36 offset:7680
	ds_read_b128 v[32:35], v32 offset:17984
	ds_read_b128 v[36:39], v36 offset:7744
	s_waitcnt lgkmcnt(2)
	v_mfma_f32_16x16x32_bf16 v[28:31], v[28:31], v[44:47], 0
	v_cvt_pk_bf16_f32 v14, v16, v17
	v_cvt_pk_bf16_f32 v15, v18, v19
	s_waitcnt lgkmcnt(0)
	v_mfma_f32_16x16x32_bf16 v[28:31], v[32:35], v[36:39], v[28:31]
	s_nop 7
	v_cndmask_b32_e64 v2, v28, 0, vcc
	v_cndmask_b32_e64 v28, 0, v29, s[4:5]
	v_cvt_pk_bf16_f32 v28, v2, v28
	v_mov_b32_e32 v2, v3
	v_cndmask_b32_e64 v29, v30, 0, s[6:7]
	v_cndmask_b32_e64 v30, v31, 0, s[8:9]
	v_cvt_pk_bf16_f32 v29, v29, v30
	v_mov_b32_e32 v30, v3
	v_mov_b32_e32 v31, v3
	s_nop 1
	v_mfma_f32_16x16x32_bf16 v[28:31], v[0:3], v[28:31], 0
	v_add_u32_e32 v0, 0x1800, v42
	ds_read2_b64 v[24:27], v0 offset0:192 offset1:196
	ds_read2_b64 v[16:19], v0 offset0:200 offset1:204
	s_waitcnt lgkmcnt(1)
	v_mfma_f32_16x16x32_bf16 v[20:23], v[20:23], v[24:27], v[28:31]
	v_mov_b32_e32 v24, v222
	s_waitcnt lgkmcnt(0)
	v_and_b32_e32 v0, 63, v24
	v_or_b32_e32 v1, s33, v0
	v_ashrrev_i32_e32 v25, 6, v24
	v_lshlrev_b32_e32 v2, 1, v1
	v_mfma_f32_16x16x32_bf16 v[12:15], v[12:15], v[16:19], v[20:23]
	v_lshl_add_u64 v[16:17], s[0:1], 0, v[2:3]
	s_barrier
	s_nop 0
	v_lshlrev_b32_e32 v20, 4, v25
	v_mad_i64_i32 v[18:19], s[4:5], v20, s48, v[16:17]
	v_mov_b32_e32 v1, v112
	v_or_b32_e32 v2, 13, v20
	v_or_b32_e32 v64, 1, v20
	v_mad_i64_i32 v[38:39], s[4:5], v2, s48, v[16:17]
	v_mov_b32_e32 v2, v125
	v_or_b32_e32 v37, 15, v20
	v_bfe_u32 v26, v24, 4, 2
	s_waitcnt vmcnt(1)
	v_lshlrev_b32_e32 v43, 16, v1
	v_mov_b32_e32 v1, v96
	v_mad_i64_i32 v[18:19], s[4:5], v64, s48, v[16:17]
	s_waitcnt vmcnt(0)
	v_lshlrev_b32_e32 v67, 16, v1
	v_mov_b32_e32 v1, v113
	s_waitcnt vmcnt(0)
	v_lshlrev_b32_e32 v66, 16, v1
	v_mov_b32_e32 v1, v97
	s_waitcnt vmcnt(0)
	v_lshlrev_b32_e32 v63, 16, v1
	v_or_b32_e32 v1, 2, v20
	v_mad_i64_i32 v[18:19], s[4:5], v1, s48, v[16:17]
	v_mov_b32_e32 v1, v114
	s_waitcnt vmcnt(0)
	v_lshlrev_b32_e32 v62, 16, v1
	v_mov_b32_e32 v1, v98
	s_waitcnt vmcnt(0)
	v_lshlrev_b32_e32 v60, 16, v1
	v_or_b32_e32 v1, 3, v20
	v_mad_i64_i32 v[18:19], s[4:5], v1, s48, v[16:17]
	v_mov_b32_e32 v1, v115
	s_waitcnt vmcnt(0)
	v_lshlrev_b32_e32 v59, 16, v1
	v_mov_b32_e32 v1, v99
	s_waitcnt vmcnt(0)
	v_lshlrev_b32_e32 v51, 16, v1
	v_or_b32_e32 v1, 4, v20
	v_mad_i64_i32 v[18:19], s[4:5], v1, s48, v[16:17]
	v_mov_b32_e32 v1, v116
	s_waitcnt vmcnt(0)
	v_lshlrev_b32_e32 v49, 16, v1
	v_mov_b32_e32 v1, v100
	s_waitcnt vmcnt(0)
	v_lshlrev_b32_e32 v48, 16, v1
	v_or_b32_e32 v1, 5, v20
	v_mad_i64_i32 v[18:19], s[4:5], v1, s48, v[16:17]
	v_mov_b32_e32 v1, v117
	s_waitcnt vmcnt(0)
	v_lshlrev_b32_e32 v47, 16, v1
	v_mov_b32_e32 v1, v101
	s_waitcnt vmcnt(0)
	v_lshlrev_b32_e32 v45, 16, v1
	v_or_b32_e32 v1, 6, v20
	v_mad_i64_i32 v[18:19], s[4:5], v1, s48, v[16:17]
	v_mov_b32_e32 v1, v118
	s_waitcnt vmcnt(0)
	v_lshlrev_b32_e32 v42, 16, v1
	v_mov_b32_e32 v1, v102
	s_waitcnt vmcnt(0)
	v_lshlrev_b32_e32 v36, 16, v1
	v_or_b32_e32 v1, 7, v20
	v_mad_i64_i32 v[18:19], s[4:5], v1, s48, v[16:17]
	v_mov_b32_e32 v1, v119
	s_waitcnt vmcnt(0)
	v_lshlrev_b32_e32 v35, 16, v1
	v_mov_b32_e32 v1, v103
	s_waitcnt vmcnt(0)
	v_lshlrev_b32_e32 v34, 16, v1
	v_or_b32_e32 v1, 8, v20
	v_mad_i64_i32 v[18:19], s[4:5], v1, s48, v[16:17]
	v_mov_b32_e32 v1, v120
	s_waitcnt vmcnt(0)
	v_lshlrev_b32_e32 v33, 16, v1
	v_mov_b32_e32 v1, v104
	s_waitcnt vmcnt(0)
	v_lshlrev_b32_e32 v32, 16, v1
	v_or_b32_e32 v1, 9, v20
	v_mad_i64_i32 v[18:19], s[4:5], v1, s48, v[16:17]
	v_mov_b32_e32 v1, v121
	s_waitcnt vmcnt(0)
	v_lshlrev_b32_e32 v31, 16, v1
	v_mov_b32_e32 v1, v105
	s_waitcnt vmcnt(0)
	v_lshlrev_b32_e32 v30, 16, v1
	v_or_b32_e32 v1, 10, v20
	v_mad_i64_i32 v[18:19], s[4:5], v1, s48, v[16:17]
	v_mov_b32_e32 v1, v122
	s_waitcnt vmcnt(0)
	v_lshlrev_b32_e32 v29, 16, v1
	v_mov_b32_e32 v1, v106
	s_waitcnt vmcnt(0)
	v_lshlrev_b32_e32 v28, 16, v1
	v_or_b32_e32 v1, 11, v20
	v_mad_i64_i32 v[18:19], s[4:5], v1, s48, v[16:17]
	v_mov_b32_e32 v1, v123
	s_waitcnt vmcnt(0)
	v_lshlrev_b32_e32 v27, 16, v1
	v_mov_b32_e32 v1, v107
	s_waitcnt vmcnt(0)
	v_lshlrev_b32_e32 v23, 16, v1
	v_or_b32_e32 v1, 12, v20
	v_mad_i64_i32 v[18:19], s[4:5], v1, s48, v[16:17]
	v_mov_b32_e32 v1, v124
	s_waitcnt vmcnt(0)
	v_lshlrev_b32_e32 v22, 16, v1
	v_mov_b32_e32 v1, v108
	v_or_b32_e32 v18, 14, v20
	v_lshlrev_b32_e32 v19, 16, v2
	v_mov_b32_e32 v2, v109
	v_mad_i64_i32 v[38:39], s[4:5], v18, s48, v[16:17]
	v_mov_b32_e32 v18, v126
	s_waitcnt vmcnt(2)
	v_lshlrev_b32_e32 v1, 16, v1
	s_waitcnt vmcnt(1)
	v_lshlrev_b32_e32 v2, 16, v2
	s_waitcnt vmcnt(0)
	v_lshlrev_b32_e32 v21, 16, v18
	v_mov_b32_e32 v18, v110
	v_mad_i64_i32 v[38:39], s[4:5], v37, s48, v[16:17]
	v_mov_b32_e32 v16, v127
	v_mov_b32_e32 v17, v111
	s_waitcnt vmcnt(2)
	v_lshlrev_b32_e32 v18, 16, v18
	s_waitcnt vmcnt(1)
	v_lshlrev_b32_e32 v16, 16, v16
	s_waitcnt vmcnt(0)
	v_lshlrev_b32_e32 v37, 16, v17
	v_add_f32_e32 v17, 0, v16
	v_add_f32_e32 v39, v17, v21
	v_add_f32_e32 v44, v39, v19
	v_add_f32_e32 v46, v44, v22
	v_add_f32_e32 v50, v46, v27
	v_add_f32_e32 v61, v50, v29
	v_add_f32_e32 v65, v61, v31
	v_add_f32_e32 v68, v65, v33
	v_add_f32_e32 v69, v68, v35
	v_add_f32_e32 v70, v69, v42
	v_add_f32_e32 v71, v70, v47
	v_add_f32_e32 v72, v71, v49
	v_add_f32_e32 v73, v72, v59
	v_add_f32_e32 v74, v73, v62
	v_add_f32_e32 v75, v74, v66
	v_add_f32_e32 v38, v75, v43
	v_mul_f32_e32 v43, 0x3fb8aa3b, v43
	v_exp_f32_e32 v43, v43
	v_mul_f32_e32 v66, 0x3fb8aa3b, v66
	v_exp_f32_e32 v66, v66
	v_mul_f32_e32 v62, 0x3fb8aa3b, v62
	v_sub_f32_e32 v76, 1.0, v43
	v_mul_lo_u32 v43, v25, s38
	v_or_b32_e32 v77, v43, v0
	v_mul_f32_e32 v43, 0x3fb8aa3b, v38
	v_exp_f32_e32 v43, v43
	v_lshl_add_u32 v77, v77, 1, 32
	v_exp_f32_e32 v62, v62
	v_mul_f32_e32 v59, 0x3fb8aa3b, v59
	v_mul_f32_e32 v67, v43, v67
	v_cvt_pk_bf16_f32 v67, v67, s0
	ds_write_b16 v77, v67
	v_min_f32_e64 v67, -v38, s40
	v_mul_f32_e32 v67, 0x3fb8aa3b, v67
	v_exp_f32_e32 v67, v67
	v_sub_f32_e32 v62, 1.0, v62
	v_exp_f32_e32 v59, v59
	v_mul_f32_e32 v49, 0x3fb8aa3b, v49
	v_mul_f32_e32 v67, v76, v67
	v_cvt_pk_bf16_f32 v67, v67, s0
	ds_write_b16 v77, v67 offset:10240
	v_sub_f32_e32 v67, v38, v38
	v_mul_f32_e32 v67, 0x3fb8aa3b, v67
	v_exp_f32_e32 v67, v67
	v_sub_f32_e32 v59, 1.0, v59
	v_exp_f32_e32 v49, v49
	v_mul_f32_e32 v47, 0x3fb8aa3b, v47
	v_mul_f32_e32 v67, v76, v67
	v_cvt_pk_bf16_f32 v67, v67, s0
	ds_write_b16 v77, v67 offset:20480
	v_sub_f32_e32 v76, 1.0, v66
	v_mad_u64_u32 v[66:67], s[4:5], v64, s39, v[0:1]
	v_mul_f32_e32 v0, 0x3fb8aa3b, v75
	v_exp_f32_e32 v0, v0
	v_sub_f32_e32 v49, 1.0, v49
	v_exp_f32_e32 v47, v47
	v_mul_f32_e32 v42, 0x3fb8aa3b, v42
	v_mul_f32_e32 v0, v0, v63
	v_cvt_pk_bf16_f32 v63, v0, s0
	v_lshl_add_u32 v0, v66, 1, 32
	ds_write_b16 v0, v63
	v_min_f32_e64 v63, -v75, s40
	v_mul_f32_e32 v63, 0x3fb8aa3b, v63
	v_exp_f32_e32 v63, v63
	v_sub_f32_e32 v47, 1.0, v47
	v_exp_f32_e32 v42, v42
	v_mul_f32_e32 v35, 0x3fb8aa3b, v35
	v_mul_f32_e32 v63, v76, v63
	v_cvt_pk_bf16_f32 v63, v63, s0
	ds_write_b16 v0, v63 offset:10240
	v_sub_f32_e32 v63, v38, v75
	v_mul_f32_e32 v63, 0x3fb8aa3b, v63
	v_exp_f32_e32 v63, v63
	v_sub_f32_e32 v42, 1.0, v42
	v_exp_f32_e32 v35, v35
	v_mul_f32_e32 v33, 0x3fb8aa3b, v33
	v_mul_f32_e32 v63, v76, v63
	v_cvt_pk_bf16_f32 v63, v63, s0
	ds_write_b16 v0, v63 offset:20480
	v_mul_f32_e32 v63, 0x3fb8aa3b, v74
	v_exp_f32_e32 v63, v63
	v_sub_f32_e32 v35, 1.0, v35
	v_exp_f32_e32 v33, v33
	v_mul_f32_e32 v31, 0x3fb8aa3b, v31
	v_mul_f32_e32 v60, v63, v60
	v_cvt_pk_bf16_f32 v60, v60, s0
	ds_write_b16 v0, v60 offset:160
	v_min_f32_e64 v60, -v74, s40
	v_mul_f32_e32 v60, 0x3fb8aa3b, v60
	v_exp_f32_e32 v60, v60
	v_sub_f32_e32 v33, 1.0, v33
	v_exp_f32_e32 v31, v31
	v_mul_f32_e32 v29, 0x3fb8aa3b, v29
	v_mul_f32_e32 v60, v62, v60
	v_cvt_pk_bf16_f32 v60, v60, s0
	ds_write_b16 v0, v60 offset:10400
	v_sub_f32_e32 v60, v38, v74
	v_mul_f32_e32 v60, 0x3fb8aa3b, v60
	v_exp_f32_e32 v60, v60
	v_sub_f32_e32 v31, 1.0, v31
	v_exp_f32_e32 v29, v29
	v_mul_f32_e32 v27, 0x3fb8aa3b, v27
	v_mul_f32_e32 v60, v62, v60
	v_cvt_pk_bf16_f32 v60, v60, s0
	ds_write_b16 v0, v60 offset:20640
	v_mul_f32_e32 v60, 0x3fb8aa3b, v73
	v_exp_f32_e32 v60, v60
	v_sub_f32_e32 v29, 1.0, v29
	v_exp_f32_e32 v27, v27
	v_mul_f32_e32 v22, 0x3fb8aa3b, v22
	v_mul_f32_e32 v51, v60, v51
	v_cvt_pk_bf16_f32 v51, v51, s0
	ds_write_b16 v0, v51 offset:320
	v_min_f32_e64 v51, -v73, s40
	v_mul_f32_e32 v51, 0x3fb8aa3b, v51
	v_exp_f32_e32 v51, v51
	v_sub_f32_e32 v27, 1.0, v27
	v_exp_f32_e32 v22, v22
	v_mul_f32_e32 v51, v59, v51
	v_cvt_pk_bf16_f32 v51, v51, s0
	ds_write_b16 v0, v51 offset:10560
	v_sub_f32_e32 v51, v38, v73
	v_mul_f32_e32 v51, 0x3fb8aa3b, v51
	v_exp_f32_e32 v51, v51
	v_sub_f32_e32 v22, 1.0, v22
	v_mul_f32_e32 v51, v59, v51
	v_cvt_pk_bf16_f32 v51, v51, s0
	ds_write_b16 v0, v51 offset:20800
	v_mul_f32_e32 v51, 0x3fb8aa3b, v72
	v_exp_f32_e32 v51, v51
	s_nop 0
	v_mul_f32_e32 v48, v51, v48
	v_cvt_pk_bf16_f32 v48, v48, s0
	ds_write_b16 v0, v48 offset:480
	v_min_f32_e64 v48, -v72, s40
	v_mul_f32_e32 v48, 0x3fb8aa3b, v48
	v_exp_f32_e32 v48, v48
	v_lshl_add_u32 v51, v25, 5, 32
	v_mul_f32_e32 v48, v49, v48
	v_cvt_pk_bf16_f32 v48, v48, s0
	ds_write_b16 v0, v48 offset:10720
	v_sub_f32_e32 v48, v38, v72
	v_mul_f32_e32 v48, 0x3fb8aa3b, v48
	v_exp_f32_e32 v48, v48
	s_nop 0
	v_mul_f32_e32 v48, v49, v48
	v_cvt_pk_bf16_f32 v48, v48, s0
	ds_write_b16 v0, v48 offset:20960
	v_mul_f32_e32 v48, 0x3fb8aa3b, v71
	v_exp_f32_e32 v48, v48
	s_nop 0
	v_mul_f32_e32 v45, v48, v45
	v_cvt_pk_bf16_f32 v45, v45, s0
	ds_write_b16 v0, v45 offset:640
	v_min_f32_e64 v45, -v71, s40
	v_mul_f32_e32 v45, 0x3fb8aa3b, v45
	v_exp_f32_e32 v45, v45
	s_nop 0
	v_mul_f32_e32 v45, v47, v45
	v_cvt_pk_bf16_f32 v45, v45, s0
	ds_write_b16 v0, v45 offset:10880
	v_sub_f32_e32 v45, v38, v71
	v_mul_f32_e32 v45, 0x3fb8aa3b, v45
	v_exp_f32_e32 v45, v45
	s_nop 0
	v_mul_f32_e32 v45, v47, v45
	v_cvt_pk_bf16_f32 v45, v45, s0
	ds_write_b16 v0, v45 offset:21120
	v_mul_f32_e32 v45, 0x3fb8aa3b, v70
	v_exp_f32_e32 v45, v45
	s_nop 0
	v_mul_f32_e32 v36, v45, v36
	v_cvt_pk_bf16_f32 v36, v36, s0
	ds_write_b16 v0, v36 offset:800
	v_min_f32_e64 v36, -v70, s40
	v_mul_f32_e32 v36, 0x3fb8aa3b, v36
	v_exp_f32_e32 v36, v36
	v_lshlrev_b32_e32 v45, 3, v26
	v_mul_f32_e32 v36, v42, v36
	v_cvt_pk_bf16_f32 v36, v36, s0
	ds_write_b16 v0, v36 offset:11040
	v_sub_f32_e32 v36, v38, v70
	v_mul_f32_e32 v36, 0x3fb8aa3b, v36
	v_exp_f32_e32 v36, v36
	s_nop 0
	v_mul_f32_e32 v36, v42, v36
	v_cvt_pk_bf16_f32 v36, v36, s0
	ds_write_b16 v0, v36 offset:21280
	v_mul_f32_e32 v36, 0x3fb8aa3b, v69
	v_exp_f32_e32 v36, v36
	s_nop 0
	v_mul_f32_e32 v34, v36, v34
	v_cvt_pk_bf16_f32 v34, v34, s0
	ds_write_b16 v0, v34 offset:960
	v_min_f32_e64 v34, -v69, s40
	v_mul_f32_e32 v34, 0x3fb8aa3b, v34
	v_exp_f32_e32 v34, v34
	s_nop 0
	v_mul_f32_e32 v34, v35, v34
	v_cvt_pk_bf16_f32 v34, v34, s0
	ds_write_b16 v0, v34 offset:11200
	v_sub_f32_e32 v34, v38, v69
	v_mul_f32_e32 v34, 0x3fb8aa3b, v34
	v_exp_f32_e32 v34, v34
	s_nop 0
	v_mul_f32_e32 v34, v35, v34
	v_cvt_pk_bf16_f32 v34, v34, s0
	ds_write_b16 v0, v34 offset:21440
	v_mul_f32_e32 v34, 0x3fb8aa3b, v68
	v_exp_f32_e32 v34, v34
	s_nop 0
	v_mul_f32_e32 v32, v34, v32
	v_cvt_pk_bf16_f32 v32, v32, s0
	ds_write_b16 v0, v32 offset:1120
	v_min_f32_e64 v32, -v68, s40
	v_mul_f32_e32 v32, 0x3fb8aa3b, v32
	v_exp_f32_e32 v32, v32
	s_nop 0
	v_mul_f32_e32 v32, v33, v32
	v_cvt_pk_bf16_f32 v32, v32, s0
	ds_write_b16 v0, v32 offset:11360
	v_sub_f32_e32 v32, v38, v68
	v_mul_f32_e32 v32, 0x3fb8aa3b, v32
	v_exp_f32_e32 v32, v32
	s_nop 0
	v_mul_f32_e32 v32, v33, v32
	v_cvt_pk_bf16_f32 v32, v32, s0
	ds_write_b16 v0, v32 offset:21600
	v_mul_f32_e32 v32, 0x3fb8aa3b, v65
	v_exp_f32_e32 v32, v32
	s_nop 0
	v_mul_f32_e32 v30, v32, v30
	v_cvt_pk_bf16_f32 v30, v30, s0
	ds_write_b16 v0, v30 offset:1280
	v_min_f32_e64 v30, -v65, s40
	v_mul_f32_e32 v30, 0x3fb8aa3b, v30
	v_exp_f32_e32 v30, v30
	s_nop 0
	v_mul_f32_e32 v30, v31, v30
	v_cvt_pk_bf16_f32 v30, v30, s0
	ds_write_b16 v0, v30 offset:11520
	v_sub_f32_e32 v30, v38, v65
	v_mul_f32_e32 v30, 0x3fb8aa3b, v30
	v_exp_f32_e32 v30, v30
	s_nop 0
	v_mul_f32_e32 v30, v31, v30
	v_cvt_pk_bf16_f32 v30, v30, s0
	ds_write_b16 v0, v30 offset:21760
	v_mul_f32_e32 v30, 0x3fb8aa3b, v61
	v_exp_f32_e32 v30, v30
	s_nop 0
	v_mul_f32_e32 v28, v30, v28
	v_cvt_pk_bf16_f32 v28, v28, s0
	ds_write_b16 v0, v28 offset:1440
	v_min_f32_e64 v28, -v61, s40
	v_mul_f32_e32 v28, 0x3fb8aa3b, v28
	v_exp_f32_e32 v28, v28
	s_nop 0
	v_mul_f32_e32 v28, v29, v28
	v_cvt_pk_bf16_f32 v28, v28, s0
	ds_write_b16 v0, v28 offset:11680
	v_sub_f32_e32 v28, v38, v61
	v_mul_f32_e32 v28, 0x3fb8aa3b, v28
	v_exp_f32_e32 v28, v28
	s_nop 0
	v_mul_f32_e32 v28, v29, v28
	v_cvt_pk_bf16_f32 v28, v28, s0
	ds_write_b16 v0, v28 offset:21920
	v_mul_f32_e32 v28, 0x3fb8aa3b, v50
	v_exp_f32_e32 v28, v28
	s_nop 0
	v_mul_f32_e32 v23, v28, v23
	v_cvt_pk_bf16_f32 v23, v23, s0
	ds_write_b16 v0, v23 offset:1600
	v_min_f32_e64 v23, -v50, s40
	v_mul_f32_e32 v23, 0x3fb8aa3b, v23
	v_exp_f32_e32 v23, v23
	s_nop 0
	v_mul_f32_e32 v23, v27, v23
	v_cvt_pk_bf16_f32 v23, v23, s0
	ds_write_b16 v0, v23 offset:11840
	v_sub_f32_e32 v23, v38, v50
	v_mul_f32_e32 v23, 0x3fb8aa3b, v23
	v_exp_f32_e32 v23, v23
	s_nop 0
	v_mul_f32_e32 v23, v27, v23
	v_cvt_pk_bf16_f32 v23, v23, s0
	ds_write_b16 v0, v23 offset:22080
	v_mul_f32_e32 v23, 0x3fb8aa3b, v46
	v_exp_f32_e32 v23, v23
	v_lshlrev_b32_e32 v27, 2, v24
	v_and_b32_e32 v50, 12, v27
	v_mul_f32_e32 v1, v23, v1
	v_cvt_pk_bf16_f32 v1, v1, s0
	ds_write_b16 v0, v1 offset:1760
	v_min_f32_e64 v1, -v46, s40
	v_mul_f32_e32 v1, 0x3fb8aa3b, v1
	v_exp_f32_e32 v1, v1
	s_nop 0
	v_mul_f32_e32 v1, v22, v1
	v_cvt_pk_bf16_f32 v1, v1, s0
	ds_write_b16 v0, v1 offset:12000
	v_sub_f32_e32 v1, v38, v46
	v_mul_f32_e32 v1, 0x3fb8aa3b, v1
	v_exp_f32_e32 v1, v1
	s_nop 0
	v_mul_f32_e32 v1, v22, v1
	v_cvt_pk_bf16_f32 v1, v1, s0
	ds_write_b16 v0, v1 offset:22240
	v_mul_f32_e32 v1, 0x3fb8aa3b, v19
	v_mul_f32_e32 v19, 0x3fb8aa3b, v44
	v_exp_f32_e32 v19, v19
	v_exp_f32_e32 v1, v1
	v_mul_f32_e32 v2, v19, v2
	v_cvt_pk_bf16_f32 v2, v2, s0
	ds_write_b16 v0, v2 offset:1920
	v_min_f32_e64 v2, -v44, s40
	v_mul_f32_e32 v2, 0x3fb8aa3b, v2
	v_exp_f32_e32 v2, v2
	v_sub_f32_e32 v1, 1.0, v1
	v_mul_f32_e32 v2, v1, v2
	v_cvt_pk_bf16_f32 v2, v2, s0
	ds_write_b16 v0, v2 offset:12160
	v_sub_f32_e32 v2, v38, v44
	v_mul_f32_e32 v2, 0x3fb8aa3b, v2
	v_exp_f32_e32 v2, v2
	v_lshlrev_b32_e32 v44, 2, v26
	v_mul_f32_e32 v1, v1, v2
	v_mul_f32_e32 v2, 0x3fb8aa3b, v39
	v_exp_f32_e32 v2, v2
	v_cvt_pk_bf16_f32 v1, v1, s0
	ds_write_b16 v0, v1 offset:22400
	v_mul_f32_e32 v1, 0x3fb8aa3b, v21
	v_mul_f32_e32 v2, v2, v18
	v_cvt_pk_bf16_f32 v2, v2, s0
	ds_write_b16 v0, v2 offset:2080
	v_min_f32_e64 v2, -v39, s40
	v_exp_f32_e32 v1, v1
	v_mul_f32_e32 v2, 0x3fb8aa3b, v2
	v_exp_f32_e32 v2, v2
	v_sub_f32_e32 v1, 1.0, v1
	v_mul_f32_e32 v2, v1, v2
	v_cvt_pk_bf16_f32 v2, v2, s0
	ds_write_b16 v0, v2 offset:12320
	v_sub_f32_e32 v2, v38, v39
	v_mul_f32_e32 v2, 0x3fb8aa3b, v2
	v_exp_f32_e32 v2, v2
	s_nop 0
	v_mul_f32_e32 v1, v1, v2
	v_mul_f32_e32 v2, 0x3fb8aa3b, v17
	v_exp_f32_e32 v2, v2
	v_cvt_pk_bf16_f32 v1, v1, s0
	ds_write_b16 v0, v1 offset:22560
	v_mul_f32_e32 v1, 0x3fb8aa3b, v16
	v_mul_f32_e32 v2, v2, v37
	v_cvt_pk_bf16_f32 v2, v2, s0
	ds_write_b16 v0, v2 offset:2240
	v_min_f32_e64 v2, -v17, s40
	v_exp_f32_e32 v1, v1
	v_mul_f32_e32 v2, 0x3fb8aa3b, v2
	v_exp_f32_e32 v2, v2
	v_sub_f32_e32 v1, 1.0, v1
	v_mul_f32_e32 v2, v1, v2
	v_cvt_pk_bf16_f32 v2, v2, s0
	ds_write_b16 v0, v2 offset:12480
	v_sub_f32_e32 v2, v38, v17
	v_mul_f32_e32 v2, 0x3fb8aa3b, v2
	v_exp_f32_e32 v2, v2
	s_nop 0
	v_mul_f32_e32 v1, v1, v2
	v_cvt_pk_bf16_f32 v1, v1, s0
	ds_write_b16 v0, v1 offset:22720
	v_add_u32_e32 v0, 32, v27
	v_ashrrev_i32_e32 v1, 3, v24
	ds_write_b32 v0, v43 offset:40960
	v_lshlrev_b32_e32 v0, 4, v24
	v_mad_i64_i32 v[16:17], s[4:5], v1, s48, v[40:41]
	v_and_b32_e32 v2, 0x70, v0
	v_lshl_add_u64 v[16:17], v[16:17], 0, s[22:23]
	v_lshl_add_u64 v[16:17], v[16:17], 0, v[2:3]
	s_waitcnt vmcnt(5)
	v_mov_b32_e32 v16, v140
	v_mov_b32_e32 v17, v141
	v_mov_b32_e32 v18, v142
	v_mov_b32_e32 v19, v143
	v_add_u32_e32 v0, 32, v2
	v_mad_u64_u32 v[22:23], s[4:5], v1, s42, v[0:1]
	v_add_u32_e32 v1, 0x100, v24
	v_ashrrev_i32_e32 v1, 3, v1
	s_waitcnt vmcnt(0)
	ds_write_b128 v22, v[16:19] offset:30720
	v_mad_i64_i32 v[16:17], s[4:5], v1, s48, v[40:41]
	v_lshl_add_u64 v[16:17], v[16:17], 0, s[22:23]
	v_lshl_add_u64 v[16:17], v[16:17], 0, v[2:3]
	v_mov_b32_e32 v16, v144
	v_mov_b32_e32 v17, v145
	v_mov_b32_e32 v18, v146
	v_mov_b32_e32 v19, v147
	v_mad_u64_u32 v[0:1], s[4:5], v1, s42, v[0:1]
	v_and_b32_e32 v2, 15, v24
	s_add_u32 s4, s12, 0x110000
	s_addc_u32 s5, s13, 0
	v_cmp_lt_u32_e32 vcc, v44, v2
	s_waitcnt vmcnt(0)
	ds_write_b128 v0, v[16:19] offset:30720
	v_or_b32_e32 v0, v20, v2
	v_lshl_add_u32 v0, v26, 8, v0
	v_ashrrev_i32_e32 v1, 31, v0
	v_lshl_add_u64 v[16:17], v[0:1], 2, s[4:5]
	s_waitcnt lgkmcnt(0)
	s_barrier
	s_waitcnt vmcnt(5)
	v_mov_b32_e32 v20, v164
	v_add_u32_e32 v16, 64, v0
	v_ashrrev_i32_e32 v17, 31, v16
	v_lshl_add_u64 v[16:17], v[16:17], 2, s[4:5]
	v_mov_b32_e32 v21, v165
	v_add_u32_e32 v16, 0x80, v0
	v_ashrrev_i32_e32 v17, 31, v16
	v_lshl_add_u64 v[16:17], v[16:17], 2, s[4:5]
	v_mov_b32_e32 v22, v166
	v_add_u32_e32 v16, 0xc0, v0
	v_ashrrev_i32_e32 v17, 31, v16
	v_lshl_add_u64 v[16:17], v[16:17], 2, s[4:5]
	v_mov_b32_e32 v23, v167
	v_add_u32_e32 v16, 0x400, v0
	v_ashrrev_i32_e32 v17, 31, v16
	v_lshl_add_u64 v[16:17], v[16:17], 2, s[4:5]
	v_mov_b32_e32 v28, v168
	v_add_u32_e32 v16, 0x440, v0
	v_ashrrev_i32_e32 v17, 31, v16
	v_lshl_add_u64 v[16:17], v[16:17], 2, s[4:5]
	v_mov_b32_e32 v29, v169
	v_add_u32_e32 v16, 0x480, v0
	v_ashrrev_i32_e32 v17, 31, v16
	v_lshl_add_u64 v[16:17], v[16:17], 2, s[4:5]
	v_mov_b32_e32 v34, v170
	v_add_u32_e32 v16, 0x4c0, v0
	v_ashrrev_i32_e32 v17, 31, v16
	v_lshl_add_u64 v[16:17], v[16:17], 2, s[4:5]
	v_mov_b32_e32 v35, v171
	v_add_u32_e32 v16, 0x800, v0
	v_ashrrev_i32_e32 v17, 31, v16
	v_lshl_add_u64 v[16:17], v[16:17], 2, s[4:5]
	v_mov_b32_e32 v36, v172
	v_add_u32_e32 v16, 0x840, v0
	v_ashrrev_i32_e32 v17, 31, v16
	v_lshl_add_u64 v[16:17], v[16:17], 2, s[4:5]
	v_mov_b32_e32 v37, v173
	v_add_u32_e32 v16, 0x880, v0
	v_ashrrev_i32_e32 v17, 31, v16
	v_lshl_add_u64 v[16:17], v[16:17], 2, s[4:5]
	v_mov_b32_e32 v38, v174
	v_add_u32_e32 v16, 0x8c0, v0
	v_ashrrev_i32_e32 v17, 31, v16
	v_lshl_add_u64 v[16:17], v[16:17], 2, s[4:5]
	v_mov_b32_e32 v39, v175
	v_add_u32_e32 v16, 0xc00, v0
	v_ashrrev_i32_e32 v17, 31, v16
	v_lshl_add_u64 v[16:17], v[16:17], 2, s[4:5]
	v_mov_b32_e32 v40, v176
	v_add_u32_e32 v16, 0xc40, v0
	v_ashrrev_i32_e32 v17, 31, v16
	v_lshl_add_u64 v[16:17], v[16:17], 2, s[4:5]
	v_mov_b32_e32 v41, v177
	v_add_u32_e32 v16, 0xc80, v0
	v_add_u32_e32 v0, 0xcc0, v0
	v_ashrrev_i32_e32 v17, 31, v16
	v_ashrrev_i32_e32 v1, 31, v0
	v_lshl_add_u64 v[16:17], v[16:17], 2, s[4:5]
	v_lshl_add_u64 v[0:1], v[0:1], 2, s[4:5]
	v_mov_b32_e32 v42, v178
	v_mov_b32_e32 v43, v179
	v_bfe_u32 v0, v24, 2, 2
	v_and_b32_e32 v24, 48, v24
	v_mul_u32_u24_e32 v16, 0x50, v2
	v_add_u32_e32 v61, 32, v24
	v_lshlrev_b32_e32 v25, 1, v16
	v_add_u32_e32 v48, v61, v25
	ds_read_b128 v[16:19], v48 offset:17920
	v_add3_u32 v60, 32, v25, v24
	v_or_b32_e32 v49, v44, v0
	ds_read_b128 v[24:27], v60 offset:7680
	v_mul_u32_u24_e32 v0, 0x50, v49
	v_or_b32_e32 v0, v0, v50
	v_lshlrev_b32_e32 v46, 1, v0
	v_add_u32_e32 v63, v51, v46
	ds_read_b64_tr_b16 v[0:1], v63 offset:38400
	s_waitcnt lgkmcnt(1)
	v_mfma_f32_16x16x32_bf16 v[16:19], v[16:19], v[24:27], 0
	ds_read_b128 v[24:27], v48 offset:17984
	ds_read_b128 v[30:33], v60 offset:7744
	v_sub_u32_e32 v59, v60, v45
	v_add_u32_e32 v62, 32, v46
	s_waitcnt lgkmcnt(0)
	v_mfma_f32_16x16x32_bf16 v[16:19], v[24:27], v[30:33], v[16:19]
	v_or_b32_e32 v24, 1, v44
	v_cmp_lt_u32_e64 s[4:5], v24, v2
	v_or_b32_e32 v24, 2, v44
	v_cmp_lt_u32_e64 s[6:7], v24, v2
	v_or_b32_e32 v24, 3, v44
	v_cmp_lt_u32_e64 s[8:9], v24, v2
	s_nop 1
	v_cndmask_b32_e64 v16, v16, 0, vcc
	v_cndmask_b32_e64 v17, v17, 0, s[4:5]
	v_cndmask_b32_e64 v18, v18, 0, s[6:7]
	v_cndmask_b32_e64 v2, v19, 0, s[8:9]
	v_cvt_pk_bf16_f32 v16, v16, v17
	v_cvt_pk_bf16_f32 v17, v18, v2
	v_mov_b32_e32 v2, v3
	v_add_u32_e32 v44, 0x1800, v59
	v_mov_b32_e32 v18, v3
	v_mov_b32_e32 v19, v3
	s_waitcnt vmcnt(14)
	v_cvt_pk_bf16_f32 v24, v20, v21
	s_waitcnt vmcnt(12)
	v_cvt_pk_bf16_f32 v25, v22, v23
	s_waitcnt vmcnt(10)
	v_cvt_pk_bf16_f32 v26, v28, v29
	ds_read2_b64 v[30:33], v44 offset0:192 offset1:196
	v_mfma_f32_16x16x32_bf16 v[16:19], v[0:3], v[16:19], 0
	v_add_u32_e32 v64, 0x1000, v59
	s_waitcnt vmcnt(8)
	v_cvt_pk_bf16_f32 v27, v34, v35
	s_waitcnt lgkmcnt(0)
	s_nop 0
	v_mfma_f32_16x16x32_bf16 v[16:19], v[24:27], v[30:33], v[16:19]
	ds_read2_b64 v[30:33], v44 offset0:200 offset1:204
	s_waitcnt vmcnt(6)
	v_cvt_pk_bf16_f32 v24, v36, v37
	s_waitcnt vmcnt(4)
	v_cvt_pk_bf16_f32 v25, v38, v39
	s_waitcnt vmcnt(2)
	v_cvt_pk_bf16_f32 v26, v40, v41
	s_waitcnt vmcnt(0)
	v_cvt_pk_bf16_f32 v27, v42, v43
	s_waitcnt lgkmcnt(0)
	s_nop 0
	v_mfma_f32_16x16x32_bf16 v[16:19], v[24:27], v[30:33], v[16:19]
	ds_read_b128 v[24:27], v61 offset:41728
	ds_read_b64_tr_b16 v[32:33], v62 offset:28224
	v_mov_b32_e32 v30, v3
	v_mov_b32_e32 v31, v3
	s_waitcnt lgkmcnt(1)
	v_pk_mul_f32 v[20:21], v[20:21], v[24:25]
	ds_read_b64_tr_b16 v[24:25], v62 offset:28160
	v_pk_mul_f32 v[22:23], v[22:23], v[26:27]
	v_mov_b32_e32 v26, v3
	v_mov_b32_e32 v27, v3
	s_waitcnt lgkmcnt(0)
	s_nop 0
	v_mfma_f32_16x16x32_bf16 v[24:27], v[24:27], v[0:3], v[20:23]
	s_nop 2
	ds_read_b128 v[20:23], v61 offset:41792
	s_waitcnt lgkmcnt(0)
	v_pk_mul_f32 v[20:21], v[28:29], v[20:21]
	ds_read_b64_tr_b16 v[28:29], v62 offset:28192
	v_pk_mul_f32 v[22:23], v[34:35], v[22:23]
	v_mov_b32_e32 v34, v3
	v_mov_b32_e32 v35, v3
	s_waitcnt lgkmcnt(0)
	v_mfma_f32_16x16x32_bf16 v[28:31], v[28:31], v[0:3], v[20:23]
	s_nop 2
	ds_read_b128 v[20:23], v61 offset:41856
	s_waitcnt lgkmcnt(0)
	v_pk_mul_f32 v[20:21], v[36:37], v[20:21]
	v_pk_mul_f32 v[22:23], v[38:39], v[22:23]
	ds_read_b64_tr_b16 v[36:37], v62 offset:28256
	v_mov_b32_e32 v38, v3
	v_mfma_f32_16x16x32_bf16 v[32:35], v[32:35], v[0:3], v[20:23]
	v_mov_b32_e32 v39, v3
	s_nop 1
	ds_read_b128 v[20:23], v61 offset:41920
	s_waitcnt lgkmcnt(0)
	v_pk_mul_f32 v[20:21], v[40:41], v[20:21]
	v_pk_mul_f32 v[22:23], v[42:43], v[22:23]
	s_nop 1
	v_mfma_f32_16x16x32_bf16 v[36:39], v[36:39], v[0:3], v[20:23]
	ds_read_b64_tr_b16 v[0:1], v63 offset:35840
	s_nop 1
	ds_read_b128 v[20:23], v48 offset:15360
	ds_read_b128 v[40:43], v60 offset:5120
	s_waitcnt lgkmcnt(0)
	v_mfma_f32_16x16x32_bf16 v[20:23], v[20:23], v[40:43], 0
	ds_read_b128 v[40:43], v48 offset:15424
	ds_read_b128 v[44:47], v60 offset:5184
	s_waitcnt lgkmcnt(0)
	v_mfma_f32_16x16x32_bf16 v[20:23], v[40:43], v[44:47], v[20:23]
	v_cvt_pk_bf16_f32 v40, v24, v25
	v_cvt_pk_bf16_f32 v41, v26, v27
	v_cvt_pk_bf16_f32 v42, v28, v29
	s_nop 4
	v_cndmask_b32_e64 v2, v20, 0, vcc
	v_cndmask_b32_e64 v20, v21, 0, s[4:5]
	v_cvt_pk_bf16_f32 v20, v2, v20
	v_mov_b32_e32 v2, v3
	v_cndmask_b32_e64 v21, v22, 0, s[6:7]
	v_cndmask_b32_e64 v22, v23, 0, s[8:9]
	v_cvt_pk_bf16_f32 v21, v21, v22
	v_mov_b32_e32 v22, v3
	v_mov_b32_e32 v23, v3
	v_cvt_pk_bf16_f32 v43, v30, v31
	ds_read2_b64 v[44:47], v64 offset0:128 offset1:132
	v_mfma_f32_16x16x32_bf16 v[20:23], v[0:3], v[20:23], 0
	s_waitcnt lgkmcnt(0)
	v_mfma_f32_16x16x32_bf16 v[20:23], v[40:43], v[44:47], v[20:23]
	v_cvt_pk_bf16_f32 v40, v32, v33
	v_cvt_pk_bf16_f32 v41, v34, v35
	v_cvt_pk_bf16_f32 v42, v36, v37
	v_cvt_pk_bf16_f32 v43, v38, v39
	ds_read2_b64 v[44:47], v64 offset0:136 offset1:140
	s_waitcnt lgkmcnt(0)
	v_mfma_f32_16x16x32_bf16 v[20:23], v[40:43], v[44:47], v[20:23]
	ds_read_b128 v[40:43], v61 offset:41472
	s_waitcnt lgkmcnt(0)
	v_pk_mul_f32 v[24:25], v[24:25], v[40:41]
	ds_read_b64_tr_b16 v[40:41], v62 offset:25600
	v_pk_mul_f32 v[26:27], v[26:27], v[42:43]
	v_mov_b32_e32 v42, v3
	v_mov_b32_e32 v43, v3
	s_waitcnt lgkmcnt(0)
	s_nop 0
	v_mfma_f32_16x16x32_bf16 v[40:43], v[40:43], v[0:3], v[24:27]
	s_nop 2
	ds_read_b128 v[24:27], v61 offset:41536
	s_waitcnt lgkmcnt(0)
	v_pk_mul_f32 v[24:25], v[28:29], v[24:25]
	ds_read_b64_tr_b16 v[28:29], v62 offset:25632
	v_pk_mul_f32 v[26:27], v[30:31], v[26:27]
	v_mov_b32_e32 v30, v3
	v_mov_b32_e32 v31, v3
	s_waitcnt lgkmcnt(0)
	s_nop 0
	v_mfma_f32_16x16x32_bf16 v[28:31], v[28:31], v[0:3], v[24:27]
	s_nop 2
	ds_read_b128 v[24:27], v61 offset:41600
	s_waitcnt lgkmcnt(0)
	v_pk_mul_f32 v[24:25], v[32:33], v[24:25]
	ds_read_b64_tr_b16 v[32:33], v62 offset:25664
	v_pk_mul_f32 v[26:27], v[34:35], v[26:27]
	v_mov_b32_e32 v34, v3
	v_mov_b32_e32 v35, v3
	s_waitcnt lgkmcnt(0)
	s_nop 0
	v_mfma_f32_16x16x32_bf16 v[32:35], v[32:35], v[0:3], v[24:27]
	s_nop 2
	ds_read_b128 v[24:27], v61 offset:41664
	s_waitcnt lgkmcnt(0)
	v_pk_mul_f32 v[24:25], v[36:37], v[24:25]
	ds_read_b64_tr_b16 v[36:37], v62 offset:25696
	v_pk_mul_f32 v[26:27], v[38:39], v[26:27]
	v_mov_b32_e32 v38, v3
	v_mov_b32_e32 v39, v3
	s_waitcnt lgkmcnt(0)
	s_nop 0
	v_mfma_f32_16x16x32_bf16 v[44:47], v[36:39], v[0:3], v[24:27]
	ds_read_b64_tr_b16 v[0:1], v63 offset:33280
	s_nop 1
	ds_read_b128 v[24:27], v48 offset:12800
	ds_read_b128 v[36:39], v60 offset:2560
	v_add_u32_e32 v63, 0x800, v59
	s_waitcnt lgkmcnt(0)
	v_mfma_f32_16x16x32_bf16 v[24:27], v[24:27], v[36:39], 0
	ds_read_b128 v[36:39], v48 offset:12864
	ds_read_b128 v[64:67], v60 offset:2624
	s_waitcnt lgkmcnt(0)
	v_mfma_f32_16x16x32_bf16 v[24:27], v[36:39], v[64:67], v[24:27]
	v_cvt_pk_bf16_f32 v36, v40, v41
	v_cvt_pk_bf16_f32 v37, v42, v43
	v_cvt_pk_bf16_f32 v38, v28, v29
	s_nop 4
	v_cndmask_b32_e64 v2, v24, 0, vcc
	v_cndmask_b32_e64 v24, v25, 0, s[4:5]
	v_cvt_pk_bf16_f32 v24, v2, v24
	v_mov_b32_e32 v2, v3
	v_cndmask_b32_e64 v25, v26, 0, s[6:7]
	v_cndmask_b32_e64 v26, v27, 0, s[8:9]
	v_cvt_pk_bf16_f32 v25, v25, v26
	v_mov_b32_e32 v26, v3
	v_mov_b32_e32 v27, v3
	v_cvt_pk_bf16_f32 v39, v30, v31
	ds_read2_b64 v[64:67], v63 offset0:64 offset1:68
	v_mfma_f32_16x16x32_bf16 v[24:27], v[0:3], v[24:27], 0
	s_waitcnt lgkmcnt(0)
	v_mfma_f32_16x16x32_bf16 v[24:27], v[36:39], v[64:67], v[24:27]
	v_cvt_pk_bf16_f32 v36, v32, v33
	v_cvt_pk_bf16_f32 v37, v34, v35
	v_cvt_pk_bf16_f32 v38, v44, v45
	v_cvt_pk_bf16_f32 v39, v46, v47
	ds_read2_b64 v[64:67], v63 offset0:72 offset1:76
	s_waitcnt lgkmcnt(0)
	v_mfma_f32_16x16x32_bf16 v[24:27], v[36:39], v[64:67], v[24:27]
	ds_read_b128 v[36:39], v61 offset:41216
	v_mov_b32_e32 v66, v3
	v_mov_b32_e32 v67, v3
	s_waitcnt lgkmcnt(0)
	v_pk_mul_f32 v[38:39], v[42:43], v[38:39]
	v_mov_b32_e32 v42, v3
	v_mov_b32_e32 v43, v3
	v_pk_mul_f32 v[36:37], v[40:41], v[36:37]
	ds_read_b64_tr_b16 v[40:41], v62 offset:23040
	ds_read_b64_tr_b16 v[64:65], v62 offset:23072
	s_waitcnt lgkmcnt(1)
	v_mfma_f32_16x16x32_bf16 v[36:39], v[40:43], v[0:3], v[36:39]
	ds_read_b128 v[40:43], v61 offset:41280
	s_waitcnt lgkmcnt(0)
	v_pk_mul_f32 v[30:31], v[30:31], v[42:43]
	v_pk_mul_f32 v[28:29], v[28:29], v[40:41]
	s_nop 3
	v_cvt_pk_bf16_f32 v36, v36, v37
	v_cvt_pk_bf16_f32 v37, v38, v39
	v_mfma_f32_16x16x32_bf16 v[40:43], v[64:67], v[0:3], v[28:31]
	s_nop 2
	ds_read_b128 v[28:31], v61 offset:41344
	s_waitcnt lgkmcnt(0)
	v_pk_mul_f32 v[28:29], v[32:33], v[28:29]
	ds_read_b64_tr_b16 v[32:33], v62 offset:23104
	v_pk_mul_f32 v[30:31], v[34:35], v[30:31]
	v_mov_b32_e32 v34, v3
	v_mov_b32_e32 v35, v3
	v_cvt_pk_bf16_f32 v38, v40, v41
	v_cvt_pk_bf16_f32 v39, v42, v43
	s_waitcnt lgkmcnt(0)
	v_mfma_f32_16x16x32_bf16 v[28:31], v[32:35], v[0:3], v[28:31]
	ds_read_b128 v[32:35], v61 offset:41408
	s_waitcnt lgkmcnt(0)
	v_pk_mul_f32 v[32:33], v[44:45], v[32:33]
	ds_read_b64_tr_b16 v[44:45], v62 offset:23136
	v_pk_mul_f32 v[34:35], v[46:47], v[34:35]
	v_mov_b32_e32 v46, v3
	v_mov_b32_e32 v47, v3
	s_nop 0
	v_cvt_pk_bf16_f32 v28, v28, v29
	v_cvt_pk_bf16_f32 v29, v30, v31
	s_waitcnt lgkmcnt(0)
	v_mfma_f32_16x16x32_bf16 v[32:35], v[44:47], v[0:3], v[32:35]
	v_mul_u32_u24_e32 v0, 0xa0, v49
	v_lshlrev_b32_e32 v1, 1, v50
	v_add3_u32 v0, v51, v0, v1
	ds_read_b64_tr_b16 v[0:1], v0 offset:30720
	ds_read_b128 v[44:47], v48 offset:10240
	ds_read_b128 v[62:65], v60
	s_waitcnt lgkmcnt(0)
	v_mfma_f32_16x16x32_bf16 v[44:47], v[44:47], v[62:65], 0
	ds_read_b128 v[48:51], v48 offset:10304
	ds_read_b128 v[60:63], v60 offset:64
	ds_read2_b64 v[40:43], v59 offset1:4
	v_cvt_pk_bf16_f32 v30, v32, v33
	s_waitcnt lgkmcnt(1)
	v_mfma_f32_16x16x32_bf16 v[44:47], v[48:51], v[60:63], v[44:47]
	v_cvt_pk_bf16_f32 v31, v34, v35
	ds_read2_b64 v[32:35], v59 offset0:8 offset1:12
	s_nop 5
	v_cndmask_b32_e64 v2, v44, 0, vcc
	v_cndmask_b32_e64 v44, v45, 0, s[4:5]
	v_cvt_pk_bf16_f32 v44, v2, v44
	v_mov_b32_e32 v2, v3
	v_cndmask_b32_e64 v45, v46, 0, s[6:7]
	v_cndmask_b32_e64 v46, v47, 0, s[8:9]
	v_cvt_pk_bf16_f32 v45, v45, v46
	v_mov_b32_e32 v46, v3
	v_mov_b32_e32 v47, v3
	v_cmp_eq_u32_e32 vcc, 0, v57
	s_nop 0
	v_mfma_f32_16x16x32_bf16 v[44:47], v[0:3], v[44:47], 0
	v_and_b32_e32 v0, 0x3fffffc0, v58
	v_lshlrev_b32_e32 v0, 2, v0
	v_lshlrev_b32_e32 v1, 2, v56
	s_waitcnt lgkmcnt(1)
	v_mfma_f32_16x16x32_bf16 v[36:39], v[36:39], v[40:43], v[44:47]
	v_add3_u32 v2, 32, v0, v1
	v_mov_b32_e32 v1, v222
	s_waitcnt lgkmcnt(0)
	v_mfma_f32_16x16x32_bf16 v[30:33], v[28:31], v[32:35], v[36:39]
	v_lshlrev_b32_e32 v1, 2, v1
	v_bitop3_b32 v1, v1, 64, v229 bitop3:0x6c
	s_nop 5
	v_pk_add_f32 v[30:31], v[54:55], v[30:31]
	v_pk_add_f32 v[28:29], v[52:53], v[32:33]
	v_mul_f32_e32 v0, v31, v31
	v_fmac_f32_e32 v0, v30, v30
	v_fmac_f32_e32 v0, v28, v28
	v_fmac_f32_e32 v0, v29, v29
	ds_bpermute_b32 v1, v1, v0
	s_waitcnt lgkmcnt(0)
	v_add_f32_e32 v0, v0, v1
	v_mov_b32_e32 v1, v222
	s_nop 0
	v_lshlrev_b32_e32 v1, 2, v1
	v_bitop3_b32 v1, v1, s18, v229 bitop3:0x6c
	ds_bpermute_b32 v1, v1, v0
	s_and_saveexec_b64 s[4:5], vcc
	s_cbranch_execz .LBB0_906
	s_waitcnt lgkmcnt(0)
	v_add_f32_e32 v0, v0, v1
	ds_write_b32 v2, v0 offset:41984

.LBB0_912:
	s_or_b64 exec, exec, s[4:5]
	v_ashrrev_i32_e32 v2, 2, v58
	v_and_b32_e32 v2, -16, v2
	v_lshl_or_b32 v12, v57, 2, v2
	v_mul_u32_u24_e32 v2, 0xe00, v56
	v_lshlrev_b32_e32 v2, 1, v2
	v_ashrrev_i32_e32 v13, 31, v12
	v_lshl_add_u64 v[14:15], s[0:1], 0, v[2:3]
	s_lshl_b32 s22, s33, 1
	s_waitcnt lgkmcnt(0)
	v_lshl_add_u64 v[4:5], v[12:13], 2, s[34:35]
	v_lshl_add_u64 v[14:15], v[14:15], 0, s[22:23]
	v_lshlrev_b64 v[12:13], 1, v[12:13]
	v_lshl_add_u64 v[14:15], v[14:15], 0, v[12:13]
	s_barrier
	s_waitcnt vmcnt(0)
	v_mov_b32_e32 v22, v184
	v_mov_b32_e32 v23, v185
	s_mov_b32 s0, 0x1c000
	v_mov_b32_e32 v4, v192
	v_mov_b32_e32 v5, v193
	v_mov_b32_e32 v6, v194
	v_mov_b32_e32 v7, v195
	v_add_co_u32_e32 v16, vcc, s0, v14
	s_mov_b32 s0, 0x38000
	s_nop 0
	v_addc_co_u32_e32 v17, vcc, 0, v15, vcc
	v_mov_b32_e32 v18, v186
	v_mov_b32_e32 v19, v187
	v_add_co_u32_e32 v16, vcc, s0, v14
	s_mov_b32 s0, 0x54000
	s_nop 0
	v_addc_co_u32_e32 v17, vcc, 0, v15, vcc
	v_mov_b32_e32 v16, v188
	v_mov_b32_e32 v17, v189
	v_add_co_u32_e32 v14, vcc, s0, v14
	v_lshl_add_u32 v2, v56, 2, 32
	s_nop 0
	v_addc_co_u32_e32 v15, vcc, 0, v15, vcc
	v_mov_b32_e32 v14, v190
	v_mov_b32_e32 v15, v191
	v_add_u32_e32 v32, 0xa400, v2
	v_or_b32_e32 v2, s11, v56
	ds_read2_b32 v[34:35], v32 offset1:16
	ds_read2_b32 v[36:37], v32 offset0:64 offset1:80
	ds_read2_b32 v[38:39], v32 offset0:128 offset1:144
	ds_read2_b32 v[40:41], v32 offset0:192 offset1:208
	v_lshlrev_b32_e32 v2, 11, v2
	s_mov_b32 s0, 0x358637bd
	s_mov_b32 s6, 0x3c800000
	s_mov_b32 s4, 0x2d94000
	s_waitcnt vmcnt(4)
	v_lshlrev_b32_e32 v33, 16, v22
	v_and_b32_e32 v44, 0xffff0000, v22
	v_lshlrev_b32_e32 v45, 16, v23
	v_and_b32_e32 v46, 0xffff0000, v23
	v_lshl_add_u64 v[22:23], s[30:31], 0, v[2:3]
	v_lshl_add_u64 v[22:23], v[22:23], 0, s[22:23]
	v_lshl_add_u64 v[42:43], v[22:23], 0, v[12:13]
	s_waitcnt lgkmcnt(3)
	v_mov_b32_e32 v22, v35
	v_mov_b32_e32 v23, v34
	s_waitcnt lgkmcnt(2)
	v_mov_b32_e32 v34, v37
	v_mov_b32_e32 v35, v36
	v_pk_add_f32 v[22:23], v[22:23], v[34:35]
	s_waitcnt lgkmcnt(1)
	v_mov_b32_e32 v34, v39
	v_mov_b32_e32 v35, v38
	v_pk_add_f32 v[22:23], v[22:23], v[34:35]
	s_waitcnt lgkmcnt(0)
	v_mov_b32_e32 v34, v41
	v_mov_b32_e32 v35, v40
	v_pk_add_f32 v[34:35], v[22:23], v[34:35]
	v_mov_b64_e32 v[22:23], s[0:1]
	v_pk_fma_f32 v[34:35], v[34:35], s[6:7], v[22:23] op_sel_hi:[1,0,0]
	s_nop 0
	v_mul_f32_e32 v36, 0x4b800000, v35
	v_cmp_gt_f32_e64 s[0:1], s19, v35
	v_cmp_gt_f32_e32 vcc, s19, v34
	s_nop 0
	v_cndmask_b32_e64 v35, v35, v36, s[0:1]
	v_rsq_f32_e32 v35, v35
	s_nop 0
	v_mul_f32_e32 v36, 0x45800000, v35
	v_cndmask_b32_e64 v35, v35, v36, s[0:1]
	v_mul_f32_e32 v30, v30, v35
	v_mul_f32_e32 v28, v28, v35
	s_waitcnt vmcnt(3)
	v_mul_f32_e32 v30, v4, v30
	v_mul_f32_e32 v31, v31, v35
	v_mul_f32_e32 v28, v6, v28
	v_mul_f32_e32 v30, v30, v33
	v_mul_f32_e32 v31, v5, v31
	v_mul_f32_e32 v33, v28, v45
	v_mul_f32_e32 v28, v29, v35
	v_mul_f32_e32 v31, v31, v44
	v_mul_f32_e32 v28, v7, v28
	v_mul_f32_e32 v29, v28, v46
	v_cvt_pk_bf16_f32 v28, v30, v31
	v_add_co_u32_e64 v30, s[0:1], s4, v42
	v_cvt_pk_bf16_f32 v29, v33, v29
	s_nop 0
	v_addc_co_u32_e64 v31, s[0:1], 0, v43, s[0:1]
	global_store_dwordx2 v[30:31], v[28:29], off offset:512
	v_mul_f32_e32 v28, 0x4b800000, v34
	v_cndmask_b32_e32 v28, v34, v28, vcc
	v_rsq_f32_e32 v28, v28
	s_waitcnt vmcnt(2)
	v_and_b32_e32 v33, 0xffff0000, v16
	v_lshlrev_b32_e32 v34, 16, v17
	v_and_b32_e32 v35, 0xffff0000, v17
	v_mul_f32_e32 v29, 0x45800000, v28
	v_cndmask_b32_e32 v28, v28, v29, vcc
	v_mul_f32_e32 v25, v25, v28
	v_lshlrev_b32_e32 v29, 16, v18
	v_mul_f32_e32 v25, v5, v25
	v_and_b32_e32 v18, 0xffff0000, v18
	v_mul_f32_e32 v18, v25, v18
	v_mul_f32_e32 v25, v26, v28
	v_mul_f32_e32 v25, v6, v25
	v_lshlrev_b32_e32 v26, 16, v19
	v_mul_f32_e32 v24, v24, v28
	v_mul_f32_e32 v25, v25, v26
	v_mul_f32_e32 v26, v27, v28
	v_mul_f32_e32 v24, v4, v24
	v_mul_f32_e32 v26, v7, v26
	v_and_b32_e32 v19, 0xffff0000, v19
	v_mul_f32_e32 v24, v24, v29
	v_mul_f32_e32 v19, v26, v19
	v_cvt_pk_bf16_f32 v18, v24, v18
	v_cvt_pk_bf16_f32 v19, v25, v19
	v_or_b32_e32 v24, 0x8000, v2
	v_mov_b32_e32 v25, v3
	v_lshl_add_u64 v[24:25], s[30:31], 0, v[24:25]
	v_lshl_add_u64 v[24:25], v[24:25], 0, s[22:23]
	v_lshl_add_u64 v[24:25], v[24:25], 0, v[12:13]
	v_add_co_u32_e32 v24, vcc, s4, v24
	v_mov_b32_e32 v17, v3
	s_nop 0
	v_addc_co_u32_e32 v25, vcc, 0, v25, vcc
	global_store_dwordx2 v[24:25], v[18:19], off offset:512
	ds_read2_b32 v[18:19], v32 offset0:32 offset1:48
	ds_read2_b32 v[24:25], v32 offset0:96 offset1:112
	ds_read2_b32 v[26:27], v32 offset0:160 offset1:176
	ds_read2_b32 v[28:29], v32 offset0:224 offset1:240
	v_lshlrev_b32_e32 v32, 16, v16
	s_waitcnt lgkmcnt(3)
	v_mov_b32_e32 v30, v19
	v_mov_b32_e32 v31, v18
	s_waitcnt lgkmcnt(2)
	v_mov_b32_e32 v18, v25
	v_mov_b32_e32 v19, v24
	v_pk_add_f32 v[18:19], v[30:31], v[18:19]
	s_waitcnt lgkmcnt(1)
	v_mov_b32_e32 v24, v27
	v_mov_b32_e32 v25, v26
	v_pk_add_f32 v[18:19], v[18:19], v[24:25]
	s_waitcnt lgkmcnt(0)
	v_mov_b32_e32 v24, v29
	v_mov_b32_e32 v25, v28
	v_pk_add_f32 v[18:19], v[18:19], v[24:25]
	v_or_b32_e32 v16, 0x10000, v2
	v_pk_fma_f32 v[18:19], v[18:19], s[6:7], v[22:23] op_sel_hi:[1,0,0]
	v_lshl_add_u64 v[16:17], s[30:31], 0, v[16:17]
	v_mul_f32_e32 v22, 0x4b800000, v19
	v_cmp_gt_f32_e64 s[0:1], s19, v19
	v_lshl_add_u64 v[16:17], v[16:17], 0, s[22:23]
	v_lshl_add_u64 v[16:17], v[16:17], 0, v[12:13]
	v_cndmask_b32_e64 v19, v19, v22, s[0:1]
	v_rsq_f32_e32 v19, v19
	v_cmp_gt_f32_e32 vcc, s19, v18
	v_or_b32_e32 v2, 0x18000, v2
	v_mul_f32_e32 v22, 0x45800000, v19
	v_cndmask_b32_e64 v19, v19, v22, s[0:1]
	v_mul_f32_e32 v10, v10, v19
	v_mul_f32_e32 v10, v6, v10
	v_mul_f32_e32 v20, v20, v19
	v_mul_f32_e32 v21, v21, v19
	v_mul_f32_e32 v22, v10, v34
	v_mul_f32_e32 v10, v11, v19
	v_mul_f32_e32 v20, v4, v20
	v_mul_f32_e32 v21, v5, v21
	v_mul_f32_e32 v10, v7, v10
	v_mul_f32_e32 v20, v20, v32
	v_mul_f32_e32 v21, v21, v33
	v_mul_f32_e32 v11, v10, v35
	v_add_co_u32_e64 v16, s[0:1], s4, v16
	v_cvt_pk_bf16_f32 v10, v20, v21
	v_cvt_pk_bf16_f32 v11, v22, v11
	v_addc_co_u32_e64 v17, s[0:1], 0, v17, s[0:1]
	global_store_dwordx2 v[16:17], v[10:11], off offset:512
	v_mul_f32_e32 v10, 0x4b800000, v18
	v_cndmask_b32_e32 v10, v18, v10, vcc
	v_rsq_f32_e32 v10, v10
	s_mov_b64 s[0:1], 0
	v_mul_f32_e32 v11, 0x45800000, v10
	v_cndmask_b32_e32 v10, v10, v11, vcc
	v_mul_f32_e32 v8, v8, v10
	v_mul_f32_e32 v4, v4, v8
	s_waitcnt vmcnt(3)
	v_lshlrev_b32_e32 v8, 16, v14
	v_mul_f32_e32 v0, v0, v10
	v_mul_f32_e32 v4, v4, v8
	v_mul_f32_e32 v8, v9, v10
	v_mul_f32_e32 v0, v6, v0
	v_lshlrev_b32_e32 v6, 16, v15
	v_mul_f32_e32 v5, v5, v8
	v_and_b32_e32 v8, 0xffff0000, v14
	v_mul_f32_e32 v6, v0, v6
	v_mul_f32_e32 v0, v1, v10
	v_mul_f32_e32 v5, v5, v8
	v_mul_f32_e32 v0, v7, v0
	v_and_b32_e32 v1, 0xffff0000, v15
	v_mul_f32_e32 v1, v0, v1
	v_cvt_pk_bf16_f32 v0, v4, v5
	v_lshl_add_u64 v[4:5], s[30:31], 0, v[2:3]
	v_lshl_add_u64 v[4:5], v[4:5], 0, s[22:23]
	v_lshl_add_u64 v[4:5], v[4:5], 0, v[12:13]
	v_add_co_u32_e32 v4, vcc, 0x2d94000, v4
	v_cvt_pk_bf16_f32 v1, v6, v1
	s_nop 0
	v_addc_co_u32_e32 v5, vcc, 0, v5, vcc
	global_store_dwordx2 v[4:5], v[0:1], off offset:512
